# GEMM phases 3/4/6/7/8: per-tile vmcnt(0) drain in the tile header (guarded the removed accumulator zeroing) dropped
# baseline (speedup 1.0000x reference)
; #define PG8_STAGE(bufoff, gbase, voff) do { _Pragma("unroll") for (int _i = 0; _i < 2; ++_i) \
;         __builtin_amdgcn_global_load_lds((const unsigned*)((const char*)(gbase) + (voff)[_i]), (LAS unsigned*)(lds + (bufoff) + ldsw + _i * 8192), 16, 0, 0); } while (0)
; #define PG8_LDA(dst, b, h) do { _Pragma("unroll") for (int m = 0; m < 4; ++m) _Pragma("unroll") for (int k = 0; k < 2; ++k) dst[m][k] = *(const LAS bf16x8*)(lds + PG8_SA(b, h) + aoff + m * 2048 + k * 1024); } while (0)
; #define PG8_LDB(dst, b, h) do { _Pragma("unroll") for (int n = 0; n < 2; ++n) _Pragma("unroll") for (int k = 0; k < 2; ++k) dst[n][k] = *(const LAS bf16x8*)(lds + PG8_SB(b, h) + boff + n * 2048 + k * 1024); } while (0)
; #define PG8_MMA(ai, bj, At, Bt) do { __builtin_amdgcn_s_setprio(1); _Pragma("unroll") for (int m = 0; m < 4; ++m) _Pragma("unroll") for (int n = 0; n < 2; ++n) _Pragma("unroll") for (int k = 0; k < 2; ++k) \
;         acc[ai][bj][m][n] = __builtin_amdgcn_mfma_f32_16x16x32_bf16(Bt[n][k], At[m][k], acc[ai][bj][m][n], 0, 0, 0); __builtin_amdgcn_s_setprio(0); } while (0)
; #define PG8_BAR __builtin_amdgcn_s_barrier()
; template <class Epi>
; __device__ __forceinline__ void gemm_phase(LAS unsigned char* lds, const Gemm g, const StaticOrder& S, const Epi& E) {
;     ...
;         const bool has_next = S.next(ui + 1, nxt);
;         const char* nA = has_next ? (const char*)g.A + (size_t)nxt.pm * tstepA : cA; const char* nB = has_next ? (const char*)g.Bt + (size_t)nxt.pn * tstepB : cB;
; #pragma nounroll
;         for (int t = 0; t < nt; t += 2) {
;             const bool last = (t == nt - 2);
;             const char* a1 = cA + (size_t)(t + 1) * kstep;
;             const char* a2 = last ? nA : cA + (size_t)(t + 2) * kstep; const char* b2 = last ? nB : cB + (size_t)(t + 2) * kstep;
;             const char* a3 = a2 + kstep; const char* b3 = b2 + kstep;
;             PG8_LDB(B0, 0, 0); PG8_LDB(B1, 0, 1); PG8_SCHED; PG8_LDA(At, 0, 0); PG8_STAGE(PG8_SA(1, 1), a1 + hstepA, voffA);
;             PG8_WAIT_V(8); PG8_WAIT_L(0); PG8_BAR; PG8_MMA(0, 0, At, B0); PG8_MMA(0, 1, At, B1); PG8_BAR; PG8_SCHED;
;             PG8_LDA(At, 0, 1); PG8_STAGE(PG8_SB(0, 0), b2, voffB); PG8_STAGE(PG8_SB(0, 1), b2 + hstepB, voffB); PG8_STAGE(PG8_SA(0, 0), a2, voffA);
;             PG8_WAIT_V(8); PG8_WAIT_L(0); PG8_BAR; PG8_MMA(1, 0, At, B0); PG8_MMA(1, 1, At, B1); PG8_BAR; PG8_SCHED;
.LBB0_456:
	s_ashr_i32 s23, s22, 31
	s_lshl_b64 s[28:29], s[22:23], 19
	s_add_u32 s28, s40, s28
	s_addc_u32 s29, s41, s29
	s_and_b64 s[30:31], s[4:5], exec
	s_cselect_b32 s1, s29, s39
	s_cselect_b32 s23, s28, s38
	s_ashr_i32 s19, s18, 31
	s_lshl_b64 s[30:31], s[18:19], 19
	s_add_u32 s30, s3, s30
	s_addc_u32 s31, s33, s31
	s_and_b64 s[52:53], s[4:5], exec
	s_cselect_b32 s19, s31, s43
	s_cselect_b32 s74, s30, s42
	s_add_u32 s38, s38, 0x40080
	s_addc_u32 s39, s39, 0
	s_add_u32 s75, s42, 0x100
	s_addc_u32 s76, s43, 0
	s_mov_b32 s77, -2
	s_waitcnt lgkmcnt(0)
	s_nop 0
	ds_read_b128 v[128:131], v173
	ds_read_b128 v[132:135], v173 offset:1024
	ds_read_b128 v[136:139], v173 offset:2048
	ds_read_b128 v[140:143], v173 offset:3072
	ds_read_b128 v[160:163], v174
	ds_read_b128 v[164:167], v174 offset:1024
	ds_read_b128 v[178:181], v174 offset:2048
	ds_read_b128 v[182:185], v174 offset:3072
	s_add_u32 s42, s38, 0xfffc0080
	s_addc_u32 s43, s39, -1
	s_cmp_eq_u32 s77, 12
	s_cselect_b32 s53, s1, s43
	s_cselect_b32 s52, s23, s42
	s_cselect_b32 s43, s19, s76
	s_cselect_b32 s42, s74, s75
	v_lshl_add_u64 v[168:169], s[38:39], 0, v[152:153]
	s_add_i32 m0, s35, 0xc000
	ds_read_b128 v[186:189], v175
	ds_read_b128 v[190:193], v175 offset:1024
	ds_read_b128 v[194:197], v175 offset:2048
	ds_read_b128 v[198:201], v175 offset:3072
	ds_read_b128 v[202:205], v175 offset:4096
	ds_read_b128 v[206:209], v175 offset:5120
	ds_read_b128 v[210:213], v175 offset:6144
	ds_read_b128 v[214:217], v175 offset:7168
	global_load_lds_dwordx4 v[168:169], off
	v_lshl_add_u64 v[168:169], s[38:39], 0, v[154:155]
	s_add_i32 m0, s35, 0xe000
	s_nop 0
	global_load_lds_dwordx4 v[168:169], off
	s_waitcnt vmcnt(8)
	s_waitcnt lgkmcnt(0)
	s_barrier
	s_setprio 1
	s_waitcnt lgkmcnt(0)
	v_mfma_f32_16x16x32_bf16 v[124:127], v[128:131], v[186:189], 0
	v_mfma_f32_16x16x32_bf16 v[120:123], v[136:139], v[186:189], 0
	v_mfma_f32_16x16x32_bf16 v[108:111], v[128:131], v[194:197], 0
	v_mfma_f32_16x16x32_bf16 v[104:107], v[136:139], v[194:197], 0
	v_mfma_f32_16x16x32_bf16 v[92:95], v[128:131], v[202:205], 0
	v_mfma_f32_16x16x32_bf16 v[88:91], v[136:139], v[202:205], 0
	v_mfma_f32_16x16x32_bf16 v[76:79], v[128:131], v[210:213], 0
	v_mfma_f32_16x16x32_bf16 v[72:75], v[136:139], v[210:213], 0
	v_mfma_f32_16x16x32_bf16 v[124:127], v[132:135], v[190:193], v[124:127]
	v_mfma_f32_16x16x32_bf16 v[120:123], v[140:143], v[190:193], v[120:123]
	v_mfma_f32_16x16x32_bf16 v[108:111], v[132:135], v[198:201], v[108:111]
	v_mfma_f32_16x16x32_bf16 v[104:107], v[140:143], v[198:201], v[104:107]
	v_mfma_f32_16x16x32_bf16 v[92:95], v[132:135], v[206:209], v[92:95]
	v_mfma_f32_16x16x32_bf16 v[88:91], v[140:143], v[206:209], v[88:91]
	v_mfma_f32_16x16x32_bf16 v[76:79], v[132:135], v[214:217], v[76:79]
	v_mfma_f32_16x16x32_bf16 v[72:75], v[140:143], v[214:217], v[72:75]
	s_setprio 0
	s_setprio 1
	v_mfma_f32_16x16x32_bf16 v[116:119], v[160:163], v[186:189], 0
	v_mfma_f32_16x16x32_bf16 v[112:115], v[178:181], v[186:189], 0
	v_mfma_f32_16x16x32_bf16 v[100:103], v[160:163], v[194:197], 0
	v_mfma_f32_16x16x32_bf16 v[96:99], v[178:181], v[194:197], 0
	v_mfma_f32_16x16x32_bf16 v[84:87], v[160:163], v[202:205], 0
	v_mfma_f32_16x16x32_bf16 v[80:83], v[178:181], v[202:205], 0
	v_mfma_f32_16x16x32_bf16 v[68:71], v[160:163], v[210:213], 0
	v_mfma_f32_16x16x32_bf16 v[64:67], v[178:181], v[210:213], 0
	v_mfma_f32_16x16x32_bf16 v[116:119], v[164:167], v[190:193], v[116:119]
	v_mfma_f32_16x16x32_bf16 v[112:115], v[182:185], v[190:193], v[112:115]
	v_mfma_f32_16x16x32_bf16 v[100:103], v[164:167], v[198:201], v[100:103]
	v_mfma_f32_16x16x32_bf16 v[96:99], v[182:185], v[198:201], v[96:99]
	v_mfma_f32_16x16x32_bf16 v[84:87], v[164:167], v[206:209], v[84:87]
	v_mfma_f32_16x16x32_bf16 v[80:83], v[182:185], v[206:209], v[80:83]
	v_mfma_f32_16x16x32_bf16 v[68:71], v[164:167], v[214:217], v[68:71]
	v_mfma_f32_16x16x32_bf16 v[64:67], v[182:185], v[214:217], v[64:67]
	s_setprio 0
	s_barrier
	s_add_i32 s78, s72, s54
	v_lshl_add_u64 v[168:169], s[42:43], 0, v[146:147]
	s_mov_b32 m0, s78
	ds_read_b128 v[186:189], v175 offset:16384
	ds_read_b128 v[190:193], v175 offset:17408
	ds_read_b128 v[194:197], v175 offset:18432
	ds_read_b128 v[198:201], v175 offset:19456
	ds_read_b128 v[202:205], v175 offset:20480
	ds_read_b128 v[206:209], v175 offset:21504
	ds_read_b128 v[210:213], v175 offset:22528
	ds_read_b128 v[214:217], v175 offset:23552
	global_load_lds_dwordx4 v[168:169], off
	s_add_i32 m0, s78, 0x2000
	s_add_u32 s78, s42, 0x40000
	v_lshl_add_u64 v[218:219], s[42:43], 0, v[150:151]
	s_addc_u32 s79, s43, 0
	s_add_i32 s80, s73, s54
	global_load_lds_dwordx4 v[218:219], off
	v_lshl_add_u64 v[220:221], s[78:79], 0, v[146:147]
	s_mov_b32 m0, s80
	v_lshl_add_u64 v[222:223], s[52:53], 0, v[148:149]
	global_load_lds_dwordx4 v[220:221], off
	v_lshl_add_u64 v[220:221], s[78:79], 0, v[150:151]
	s_add_i32 m0, s80, 0x2000
	s_nop 0
	global_load_lds_dwordx4 v[220:221], off
	v_lshl_add_u64 v[220:221], s[52:53], 0, v[144:145]
	s_mov_b32 m0, s35
	s_nop 0
	global_load_lds_dwordx4 v[220:221], off
	s_mov_b32 m0, s55
	s_nop 0
	global_load_lds_dwordx4 v[222:223], off
	s_waitcnt vmcnt(8)
	s_waitcnt lgkmcnt(0)
	s_barrier
; #define PG8_STAGE(bufoff, gbase, voff) do { _Pragma("unroll") for (int _i = 0; _i < 2; ++_i) \
;         __builtin_amdgcn_global_load_lds((const unsigned*)((const char*)(gbase) + (voff)[_i]), (LAS unsigned*)(lds + (bufoff) + ldsw + _i * 8192), 16, 0, 0); } while (0)
; #define PG8_LDA(dst, b, h) do { _Pragma("unroll") for (int m = 0; m < 4; ++m) _Pragma("unroll") for (int k = 0; k < 2; ++k) dst[m][k] = *(const LAS bf16x8*)(lds + PG8_SA(b, h) + aoff + m * 2048 + k * 1024); } while (0)
; #define PG8_LDB(dst, b, h) do { _Pragma("unroll") for (int n = 0; n < 2; ++n) _Pragma("unroll") for (int k = 0; k < 2; ++k) dst[n][k] = *(const LAS bf16x8*)(lds + PG8_SB(b, h) + boff + n * 2048 + k * 1024); } while (0)
; #define PG8_MMA(ai, bj, At, Bt) do { __builtin_amdgcn_s_setprio(1); _Pragma("unroll") for (int m = 0; m < 4; ++m) _Pragma("unroll") for (int n = 0; n < 2; ++n) _Pragma("unroll") for (int k = 0; k < 2; ++k) \
;         acc[ai][bj][m][n] = __builtin_amdgcn_mfma_f32_16x16x32_bf16(Bt[n][k], At[m][k], acc[ai][bj][m][n], 0, 0, 0); __builtin_amdgcn_s_setprio(0); } while (0)
; #define PG8_WAIT_V(n) asm volatile("s_waitcnt vmcnt(" #n ")" ::: "memory")
; #define PG8_WAIT_L(n) asm volatile("s_waitcnt lgkmcnt(" #n ")" ::: "memory")
; #define PG8_BAR __builtin_amdgcn_s_barrier()
; #define PG8_SCHED __builtin_amdgcn_sched_barrier(0)
; template <class Epi>
; __device__ __forceinline__ void gemm_phase(LAS unsigned char* lds, const Gemm g, const StaticOrder& S, const Epi& E) {
;     ...
;             PG8_WAIT_V(8); PG8_WAIT_L(0); PG8_BAR; PG8_MMA(1, 0, At, B0); PG8_MMA(1, 1, At, B1); PG8_BAR; PG8_SCHED;
;             PG8_LDB(B0, 1, 0); PG8_LDB(B1, 1, 1); PG8_SCHED; PG8_LDA(At, 1, 0); PG8_STAGE(PG8_SA(0, 1), a2 + hstepA, voffA);
;             PG8_WAIT_V(8); PG8_WAIT_L(0); PG8_BAR; PG8_MMA(0, 0, At, B0); PG8_MMA(0, 1, At, B1); PG8_BAR; PG8_SCHED;
;             PG8_LDA(At, 1, 1); PG8_STAGE(PG8_SB(1, 0), b3, voffB); PG8_STAGE(PG8_SB(1, 1), b3 + hstepB, voffB); PG8_STAGE(PG8_SA(1, 0), a3, voffA);
;             PG8_WAIT_V(8); PG8_WAIT_L(0); PG8_BAR; PG8_MMA(1, 0, At, B0); PG8_MMA(1, 1, At, B1); PG8_BAR; PG8_SCHED;
	s_setprio 1
	s_waitcnt lgkmcnt(0)
	v_mfma_f32_16x16x32_bf16 v[60:63], v[128:131], v[186:189], 0
	v_mfma_f32_16x16x32_bf16 v[56:59], v[136:139], v[186:189], 0
	v_mfma_f32_16x16x32_bf16 v[44:47], v[128:131], v[194:197], 0
	v_mfma_f32_16x16x32_bf16 v[40:43], v[136:139], v[194:197], 0
	v_mfma_f32_16x16x32_bf16 v[28:31], v[128:131], v[202:205], 0
	v_mfma_f32_16x16x32_bf16 v[24:27], v[136:139], v[202:205], 0
	v_mfma_f32_16x16x32_bf16 v[12:15], v[128:131], v[210:213], 0
	v_mfma_f32_16x16x32_bf16 v[8:11], v[136:139], v[210:213], 0
	v_mfma_f32_16x16x32_bf16 v[60:63], v[132:135], v[190:193], v[60:63]
	v_mfma_f32_16x16x32_bf16 v[56:59], v[140:143], v[190:193], v[56:59]
	v_mfma_f32_16x16x32_bf16 v[44:47], v[132:135], v[198:201], v[44:47]
	v_mfma_f32_16x16x32_bf16 v[40:43], v[140:143], v[198:201], v[40:43]
	v_mfma_f32_16x16x32_bf16 v[28:31], v[132:135], v[206:209], v[28:31]
	v_mfma_f32_16x16x32_bf16 v[24:27], v[140:143], v[206:209], v[24:27]
	v_mfma_f32_16x16x32_bf16 v[12:15], v[132:135], v[214:217], v[12:15]
	v_mfma_f32_16x16x32_bf16 v[8:11], v[140:143], v[214:217], v[8:11]
	s_setprio 0
	s_setprio 1
	v_mfma_f32_16x16x32_bf16 v[52:55], v[160:163], v[186:189], 0
	v_mfma_f32_16x16x32_bf16 v[48:51], v[178:181], v[186:189], 0
	v_mfma_f32_16x16x32_bf16 v[36:39], v[160:163], v[194:197], 0
	v_mfma_f32_16x16x32_bf16 v[32:35], v[178:181], v[194:197], 0
	v_mfma_f32_16x16x32_bf16 v[20:23], v[160:163], v[202:205], 0
	v_mfma_f32_16x16x32_bf16 v[16:19], v[178:181], v[202:205], 0
	v_mfma_f32_16x16x32_bf16 v[4:7], v[160:163], v[210:213], 0
	v_mfma_f32_16x16x32_bf16 v[0:3], v[178:181], v[210:213], 0
	v_mfma_f32_16x16x32_bf16 v[52:55], v[164:167], v[190:193], v[52:55]
	v_mfma_f32_16x16x32_bf16 v[48:51], v[182:185], v[190:193], v[48:51]
	v_mfma_f32_16x16x32_bf16 v[36:39], v[164:167], v[198:201], v[36:39]
	v_mfma_f32_16x16x32_bf16 v[32:35], v[182:185], v[198:201], v[32:35]
	v_mfma_f32_16x16x32_bf16 v[20:23], v[164:167], v[206:209], v[20:23]
	v_mfma_f32_16x16x32_bf16 v[16:19], v[182:185], v[206:209], v[16:19]
	v_mfma_f32_16x16x32_bf16 v[4:7], v[164:167], v[214:217], v[4:7]
	v_mfma_f32_16x16x32_bf16 v[0:3], v[182:185], v[214:217], v[0:3]
	s_setprio 0
	s_barrier
	s_add_i32 s78, 0, 0x18000
	s_add_i32 s79, 0, 0x1c000
	v_add_u32_e32 v140, s78, v172
	v_add_u32_e32 v182, s79, v172
	ds_read_b128 v[128:131], v140
	ds_read_b128 v[132:135], v140 offset:1024
	ds_read_b128 v[136:139], v140 offset:2048
	ds_read_b128 v[140:143], v140 offset:3072
	ds_read_b128 v[160:163], v182
	ds_read_b128 v[164:167], v182 offset:1024
	ds_read_b128 v[178:181], v182 offset:2048
	ds_read_b128 v[182:185], v182 offset:3072
	s_add_u32 s52, s52, 0x40000
	s_addc_u32 s53, s53, 0
	s_mov_b32 m0, s56
	v_lshl_add_u64 v[226:227], s[52:53], 0, v[144:145]
	ds_read_b128 v[186:189], v175 offset:32768
	ds_read_b128 v[190:193], v175 offset:33792
	ds_read_b128 v[194:197], v175 offset:34816
	ds_read_b128 v[198:201], v175 offset:35840
	ds_read_b128 v[202:205], v175 offset:36864
	ds_read_b128 v[206:209], v175 offset:37888
	ds_read_b128 v[210:213], v175 offset:38912
	ds_read_b128 v[214:217], v175 offset:39936
	global_load_lds_dwordx4 v[226:227], off
	v_lshl_add_u64 v[226:227], s[52:53], 0, v[148:149]
	s_mov_b32 m0, s57
	s_nop 0
	global_load_lds_dwordx4 v[226:227], off
	s_waitcnt vmcnt(8)
	s_waitcnt lgkmcnt(0)
	s_barrier
	s_setprio 1
	s_waitcnt lgkmcnt(0)
	v_mfma_f32_16x16x32_bf16 v[124:127], v[128:131], v[186:189], v[124:127]
	v_mfma_f32_16x16x32_bf16 v[120:123], v[136:139], v[186:189], v[120:123]
	v_mfma_f32_16x16x32_bf16 v[108:111], v[128:131], v[194:197], v[108:111]
	v_mfma_f32_16x16x32_bf16 v[104:107], v[136:139], v[194:197], v[104:107]
	v_mfma_f32_16x16x32_bf16 v[92:95], v[128:131], v[202:205], v[92:95]
	v_mfma_f32_16x16x32_bf16 v[88:91], v[136:139], v[202:205], v[88:91]
	v_mfma_f32_16x16x32_bf16 v[76:79], v[128:131], v[210:213], v[76:79]
	v_mfma_f32_16x16x32_bf16 v[72:75], v[136:139], v[210:213], v[72:75]
	v_mfma_f32_16x16x32_bf16 v[124:127], v[132:135], v[190:193], v[124:127]
	v_mfma_f32_16x16x32_bf16 v[120:123], v[140:143], v[190:193], v[120:123]
	v_mfma_f32_16x16x32_bf16 v[108:111], v[132:135], v[198:201], v[108:111]
	v_mfma_f32_16x16x32_bf16 v[104:107], v[140:143], v[198:201], v[104:107]
	v_mfma_f32_16x16x32_bf16 v[92:95], v[132:135], v[206:209], v[92:95]
	v_mfma_f32_16x16x32_bf16 v[88:91], v[140:143], v[206:209], v[88:91]
	v_mfma_f32_16x16x32_bf16 v[76:79], v[132:135], v[214:217], v[76:79]
	v_mfma_f32_16x16x32_bf16 v[72:75], v[140:143], v[214:217], v[72:75]
	s_setprio 0
	s_setprio 1
	v_mfma_f32_16x16x32_bf16 v[116:119], v[160:163], v[186:189], v[116:119]
	v_mfma_f32_16x16x32_bf16 v[112:115], v[178:181], v[186:189], v[112:115]
	v_mfma_f32_16x16x32_bf16 v[100:103], v[160:163], v[194:197], v[100:103]
	v_mfma_f32_16x16x32_bf16 v[96:99], v[178:181], v[194:197], v[96:99]
	v_mfma_f32_16x16x32_bf16 v[84:87], v[160:163], v[202:205], v[84:87]
	v_mfma_f32_16x16x32_bf16 v[80:83], v[178:181], v[202:205], v[80:83]
	v_mfma_f32_16x16x32_bf16 v[68:71], v[160:163], v[210:213], v[68:71]
	v_mfma_f32_16x16x32_bf16 v[64:67], v[178:181], v[210:213], v[64:67]
	v_mfma_f32_16x16x32_bf16 v[116:119], v[164:167], v[190:193], v[116:119]
	v_mfma_f32_16x16x32_bf16 v[112:115], v[182:185], v[190:193], v[112:115]
	v_mfma_f32_16x16x32_bf16 v[100:103], v[164:167], v[198:201], v[100:103]
	v_mfma_f32_16x16x32_bf16 v[96:99], v[182:185], v[198:201], v[96:99]
	v_mfma_f32_16x16x32_bf16 v[84:87], v[164:167], v[206:209], v[84:87]
	v_mfma_f32_16x16x32_bf16 v[80:83], v[182:185], v[206:209], v[80:83]
	v_mfma_f32_16x16x32_bf16 v[68:71], v[164:167], v[214:217], v[68:71]
	v_mfma_f32_16x16x32_bf16 v[64:67], v[182:185], v[214:217], v[64:67]
	s_setprio 0
	s_barrier
; #define PG8_STAGE(bufoff, gbase, voff) do { _Pragma("unroll") for (int _i = 0; _i < 2; ++_i) \
;         __builtin_amdgcn_global_load_lds((const unsigned*)((const char*)(gbase) + (voff)[_i]), (LAS unsigned*)(lds + (bufoff) + ldsw + _i * 8192), 16, 0, 0); } while (0)
; #define PG8_LDA(dst, b, h) do { _Pragma("unroll") for (int m = 0; m < 4; ++m) _Pragma("unroll") for (int k = 0; k < 2; ++k) dst[m][k] = *(const LAS bf16x8*)(lds + PG8_SA(b, h) + aoff + m * 2048 + k * 1024); } while (0)
; #define PG8_MMA(ai, bj, At, Bt) do { __builtin_amdgcn_s_setprio(1); _Pragma("unroll") for (int m = 0; m < 4; ++m) _Pragma("unroll") for (int n = 0; n < 2; ++n) _Pragma("unroll") for (int k = 0; k < 2; ++k) \
;         acc[ai][bj][m][n] = __builtin_amdgcn_mfma_f32_16x16x32_bf16(Bt[n][k], At[m][k], acc[ai][bj][m][n], 0, 0, 0); __builtin_amdgcn_s_setprio(0); } while (0)
; #define PG8_WAIT_V(n) asm volatile("s_waitcnt vmcnt(" #n ")" ::: "memory")
; #define PG8_WAIT_L(n) asm volatile("s_waitcnt lgkmcnt(" #n ")" ::: "memory")
; #define PG8_BAR __builtin_amdgcn_s_barrier()
; #define PG8_SCHED __builtin_amdgcn_sched_barrier(0)
; template <class Epi>
; __device__ __forceinline__ void gemm_phase(LAS unsigned char* lds, const Gemm g, const StaticOrder& S, const Epi& E) {
;     ...
;             PG8_LDA(At, 1, 1); PG8_STAGE(PG8_SB(1, 0), b3, voffB); PG8_STAGE(PG8_SB(1, 1), b3 + hstepB, voffB); PG8_STAGE(PG8_SA(1, 0), a3, voffA);
;             PG8_WAIT_V(8); PG8_WAIT_L(0); PG8_BAR; PG8_MMA(1, 0, At, B0); PG8_MMA(1, 1, At, B1); PG8_BAR; PG8_SCHED;
;         }
	s_add_i32 s52, s78, s54
	v_lshl_add_u64 v[168:169], v[168:169], 0, s[12:13]
	s_mov_b32 m0, s52
	ds_read_b128 v[186:189], v175 offset:49152
	ds_read_b128 v[190:193], v175 offset:50176
	ds_read_b128 v[194:197], v175 offset:51200
	ds_read_b128 v[198:201], v175 offset:52224
	ds_read_b128 v[202:205], v175 offset:53248
	ds_read_b128 v[206:209], v175 offset:54272
	ds_read_b128 v[210:213], v175 offset:55296
	ds_read_b128 v[214:217], v175 offset:56320
	global_load_lds_dwordx4 v[168:169], off
	s_add_i32 m0, s52, 0x2000
	s_add_u32 s42, s42, 0x40080
	v_lshl_add_u64 v[168:169], v[218:219], 0, s[12:13]
	s_addc_u32 s43, s43, 0
	s_add_i32 s52, s79, s54
	global_load_lds_dwordx4 v[168:169], off
	v_lshl_add_u64 v[168:169], s[42:43], 0, v[146:147]
	s_mov_b32 m0, s52
	s_nop 0
	global_load_lds_dwordx4 v[168:169], off
	v_lshl_add_u64 v[168:169], s[42:43], 0, v[150:151]
	s_add_i32 m0, s52, 0x2000
	s_nop 0
	global_load_lds_dwordx4 v[168:169], off
	v_lshl_add_u64 v[168:169], v[220:221], 0, s[12:13]
	s_mov_b32 m0, s65
	s_nop 0
	global_load_lds_dwordx4 v[168:169], off
	v_lshl_add_u64 v[168:169], v[222:223], 0, s[12:13]
	s_mov_b32 m0, s68
	s_nop 0
	global_load_lds_dwordx4 v[168:169], off
	s_waitcnt vmcnt(8)
	s_waitcnt lgkmcnt(0)
	s_barrier
	s_setprio 1
	s_waitcnt lgkmcnt(0)
	v_mfma_f32_16x16x32_bf16 v[60:63], v[128:131], v[186:189], v[60:63]
	v_mfma_f32_16x16x32_bf16 v[56:59], v[136:139], v[186:189], v[56:59]
	v_mfma_f32_16x16x32_bf16 v[44:47], v[128:131], v[194:197], v[44:47]
	v_mfma_f32_16x16x32_bf16 v[40:43], v[136:139], v[194:197], v[40:43]
	v_mfma_f32_16x16x32_bf16 v[28:31], v[128:131], v[202:205], v[28:31]
	v_mfma_f32_16x16x32_bf16 v[24:27], v[136:139], v[202:205], v[24:27]
	v_mfma_f32_16x16x32_bf16 v[12:15], v[128:131], v[210:213], v[12:15]
	v_mfma_f32_16x16x32_bf16 v[8:11], v[136:139], v[210:213], v[8:11]
	v_mfma_f32_16x16x32_bf16 v[60:63], v[132:135], v[190:193], v[60:63]
	v_mfma_f32_16x16x32_bf16 v[56:59], v[140:143], v[190:193], v[56:59]
	v_mfma_f32_16x16x32_bf16 v[44:47], v[132:135], v[198:201], v[44:47]
	v_mfma_f32_16x16x32_bf16 v[40:43], v[140:143], v[198:201], v[40:43]
	v_mfma_f32_16x16x32_bf16 v[28:31], v[132:135], v[206:209], v[28:31]
	v_mfma_f32_16x16x32_bf16 v[24:27], v[140:143], v[206:209], v[24:27]
	v_mfma_f32_16x16x32_bf16 v[12:15], v[132:135], v[214:217], v[12:15]
	v_mfma_f32_16x16x32_bf16 v[8:11], v[140:143], v[214:217], v[8:11]
	s_setprio 0
	s_setprio 1
	v_mfma_f32_16x16x32_bf16 v[52:55], v[160:163], v[186:189], v[52:55]
	v_mfma_f32_16x16x32_bf16 v[48:51], v[178:181], v[186:189], v[48:51]
	v_mfma_f32_16x16x32_bf16 v[36:39], v[160:163], v[194:197], v[36:39]
	v_mfma_f32_16x16x32_bf16 v[32:35], v[178:181], v[194:197], v[32:35]
	v_mfma_f32_16x16x32_bf16 v[20:23], v[160:163], v[202:205], v[20:23]
	v_mfma_f32_16x16x32_bf16 v[16:19], v[178:181], v[202:205], v[16:19]
	v_mfma_f32_16x16x32_bf16 v[4:7], v[160:163], v[210:213], v[4:7]
	v_mfma_f32_16x16x32_bf16 v[0:3], v[178:181], v[210:213], v[0:3]
	v_mfma_f32_16x16x32_bf16 v[52:55], v[164:167], v[190:193], v[52:55]
	v_mfma_f32_16x16x32_bf16 v[48:51], v[182:185], v[190:193], v[48:51]
	v_mfma_f32_16x16x32_bf16 v[36:39], v[164:167], v[198:201], v[36:39]
	v_mfma_f32_16x16x32_bf16 v[32:35], v[182:185], v[198:201], v[32:35]
	v_mfma_f32_16x16x32_bf16 v[20:23], v[164:167], v[206:209], v[20:23]
	v_mfma_f32_16x16x32_bf16 v[16:19], v[182:185], v[206:209], v[16:19]
	v_mfma_f32_16x16x32_bf16 v[4:7], v[164:167], v[214:217], v[4:7]
	v_mfma_f32_16x16x32_bf16 v[0:3], v[182:185], v[214:217], v[0:3]
	s_setprio 0
	s_barrier
	s_add_i32 s77, s77, 2
	s_add_u32 s38, s38, 0x100
	s_addc_u32 s39, s39, 0
	s_add_u32 s75, s75, 0x100
	s_addc_u32 s76, s76, 0
	s_cmp_gt_u32 s77, 13

; #define PG8_STAGE(bufoff, gbase, voff) do { _Pragma("unroll") for (int _i = 0; _i < 2; ++_i) \
;         __builtin_amdgcn_global_load_lds((const unsigned*)((const char*)(gbase) + (voff)[_i]), (LAS unsigned*)(lds + (bufoff) + ldsw + _i * 8192), 16, 0, 0); } while (0)
; #define PG8_LDA(dst, b, h) do { _Pragma("unroll") for (int m = 0; m < 4; ++m) _Pragma("unroll") for (int k = 0; k < 2; ++k) dst[m][k] = *(const LAS bf16x8*)(lds + PG8_SA(b, h) + aoff + m * 2048 + k * 1024); } while (0)
; #define PG8_LDB(dst, b, h) do { _Pragma("unroll") for (int n = 0; n < 2; ++n) _Pragma("unroll") for (int k = 0; k < 2; ++k) dst[n][k] = *(const LAS bf16x8*)(lds + PG8_SB(b, h) + boff + n * 2048 + k * 1024); } while (0)
; #define PG8_MMA(ai, bj, At, Bt) do { __builtin_amdgcn_s_setprio(1); _Pragma("unroll") for (int m = 0; m < 4; ++m) _Pragma("unroll") for (int n = 0; n < 2; ++n) _Pragma("unroll") for (int k = 0; k < 2; ++k) \
;         acc[ai][bj][m][n] = __builtin_amdgcn_mfma_f32_16x16x32_bf16(Bt[n][k], At[m][k], acc[ai][bj][m][n], 0, 0, 0); __builtin_amdgcn_s_setprio(0); } while (0)
; #define PG8_BAR __builtin_amdgcn_s_barrier()
; template <class Epi>
; __device__ __forceinline__ void gemm_phase(LAS unsigned char* lds, const Gemm g, const StaticOrder& S, const Epi& E) {
;     ...
;         const bool has_next = S.next(ui + 1, nxt);
;         const char* nA = has_next ? (const char*)g.A + (size_t)nxt.pm * tstepA : cA; const char* nB = has_next ? (const char*)g.Bt + (size_t)nxt.pn * tstepB : cB;
; #pragma nounroll
;         for (int t = 0; t < nt; t += 2) {
;             const bool last = (t == nt - 2);
;             const char* a1 = cA + (size_t)(t + 1) * kstep;
;             const char* a2 = last ? nA : cA + (size_t)(t + 2) * kstep; const char* b2 = last ? nB : cB + (size_t)(t + 2) * kstep;
;             const char* a3 = a2 + kstep; const char* b3 = b2 + kstep;
;             PG8_LDB(B0, 0, 0); PG8_LDB(B1, 0, 1); PG8_SCHED; PG8_LDA(At, 0, 0); PG8_STAGE(PG8_SA(1, 1), a1 + hstepA, voffA);
;             PG8_WAIT_V(8); PG8_WAIT_L(0); PG8_BAR; PG8_MMA(0, 0, At, B0); PG8_MMA(0, 1, At, B1); PG8_BAR; PG8_SCHED;
;             PG8_LDA(At, 0, 1); PG8_STAGE(PG8_SB(0, 0), b2, voffB); PG8_STAGE(PG8_SB(0, 1), b2 + hstepB, voffB); PG8_STAGE(PG8_SA(0, 0), a2, voffA);
;             PG8_WAIT_V(8); PG8_WAIT_L(0); PG8_BAR; PG8_MMA(1, 0, At, B0); PG8_MMA(1, 1, At, B1); PG8_BAR; PG8_SCHED;
.LBB0_545:
	s_ashr_i32 s71, s70, 31
	s_lshl_b64 s[12:13], s[70:71], 19
	s_add_u32 s72, s24, s12
	s_addc_u32 s73, s25, s13
	s_and_b64 s[12:13], s[4:5], exec
	s_cselect_b32 s1, s73, s9
	s_cselect_b32 s7, s72, s8
	s_ashr_i32 s69, s68, 31
	s_lshl_b64 s[12:13], s[68:69], 19
	s_add_u32 s74, s3, s12
	s_addc_u32 s75, s33, s13
	s_and_b64 s[12:13], s[4:5], exec
	s_cselect_b32 s69, s75, s11
	s_cselect_b32 s71, s74, s10
	s_add_u32 s8, s8, 0x40080
	s_addc_u32 s9, s9, 0
	s_add_u32 s76, s10, 0x100
	s_addc_u32 s77, s11, 0
	s_mov_b32 s89, -2
	s_nop 0
	v_lshl_add_u32 v248, s6, 8, v151
	v_add_u32_e32 v248, s65, v248
	v_ashrrev_i32_e32 v249, 31, v248
	v_lshl_add_u64 v[248:249], v[248:249], 2, s[22:23]
	global_load_dword v240, v[248:249], off
	global_load_dword v241, v[248:249], off offset:64
	global_load_dword v242, v[248:249], off offset:128
	global_load_dword v243, v[248:249], off offset:192
	global_load_dword v244, v[248:249], off offset:512
	global_load_dword v245, v[248:249], off offset:576
	global_load_dword v246, v[248:249], off offset:640
	global_load_dword v247, v[248:249], off offset:704
	ds_read_b128 v[146:149], v162
	ds_read_b128 v[166:169], v162 offset:1024
	ds_read_b128 v[170:173], v162 offset:2048
	ds_read_b128 v[178:181], v162 offset:3072
	ds_read_b128 v[182:185], v163
	ds_read_b128 v[186:189], v163 offset:1024
	ds_read_b128 v[190:193], v163 offset:2048
	ds_read_b128 v[194:197], v163 offset:3072
	s_add_u32 s10, s8, 0xfffc0080
	s_addc_u32 s11, s9, -1
	s_cmp_eq_u32 s89, 12
	s_cselect_b32 s13, s1, s11
	s_cselect_b32 s12, s7, s10
	s_cselect_b32 s11, s69, s77
	s_cselect_b32 s10, s71, s76
	v_lshl_add_u64 v[174:175], s[8:9], 0, v[138:139]
	s_add_i32 m0, s43, 0xc000
	ds_read_b128 v[198:201], v164
	ds_read_b128 v[202:205], v164 offset:1024
	ds_read_b128 v[206:209], v164 offset:2048
	ds_read_b128 v[210:213], v164 offset:3072
	ds_read_b128 v[214:217], v164 offset:4096
	ds_read_b128 v[218:221], v164 offset:5120
	ds_read_b128 v[226:229], v164 offset:6144
	ds_read_b128 v[230:233], v164 offset:7168
	global_load_lds_dwordx4 v[174:175], off
	v_lshl_add_u64 v[174:175], s[8:9], 0, v[140:141]
	s_add_i32 m0, s43, 0xe000
	s_nop 0
	global_load_lds_dwordx4 v[174:175], off
	s_waitcnt vmcnt(8)
	s_waitcnt lgkmcnt(0)
	s_barrier
	s_setprio 1
	s_waitcnt lgkmcnt(0)
	v_mfma_f32_16x16x32_bf16 v[124:127], v[146:149], v[198:201], 0
	v_mfma_f32_16x16x32_bf16 v[120:123], v[170:173], v[198:201], 0
	v_mfma_f32_16x16x32_bf16 v[112:115], v[146:149], v[206:209], 0
	v_mfma_f32_16x16x32_bf16 v[104:107], v[170:173], v[206:209], 0
	v_mfma_f32_16x16x32_bf16 v[100:103], v[146:149], v[214:217], 0
	v_mfma_f32_16x16x32_bf16 v[92:95], v[170:173], v[214:217], 0
	v_mfma_f32_16x16x32_bf16 v[84:87], v[146:149], v[226:229], 0
	v_mfma_f32_16x16x32_bf16 v[76:79], v[170:173], v[226:229], 0
	v_mfma_f32_16x16x32_bf16 v[124:127], v[166:169], v[202:205], v[124:127]
	v_mfma_f32_16x16x32_bf16 v[120:123], v[178:181], v[202:205], v[120:123]
	v_mfma_f32_16x16x32_bf16 v[112:115], v[166:169], v[210:213], v[112:115]
	v_mfma_f32_16x16x32_bf16 v[104:107], v[178:181], v[210:213], v[104:107]
	v_mfma_f32_16x16x32_bf16 v[100:103], v[166:169], v[218:221], v[100:103]
	v_mfma_f32_16x16x32_bf16 v[92:95], v[178:181], v[218:221], v[92:95]
	v_mfma_f32_16x16x32_bf16 v[84:87], v[166:169], v[230:233], v[84:87]
	v_mfma_f32_16x16x32_bf16 v[76:79], v[178:181], v[230:233], v[76:79]
	s_setprio 0
	s_setprio 1
	v_mfma_f32_16x16x32_bf16 v[116:119], v[182:185], v[198:201], 0
	v_mfma_f32_16x16x32_bf16 v[108:111], v[190:193], v[198:201], 0
	v_mfma_f32_16x16x32_bf16 v[96:99], v[182:185], v[206:209], 0
	v_mfma_f32_16x16x32_bf16 v[88:91], v[190:193], v[206:209], 0
	v_mfma_f32_16x16x32_bf16 v[80:83], v[182:185], v[214:217], 0
	v_mfma_f32_16x16x32_bf16 v[72:75], v[190:193], v[214:217], 0
	v_mfma_f32_16x16x32_bf16 v[68:71], v[182:185], v[226:229], 0
	v_mfma_f32_16x16x32_bf16 v[64:67], v[190:193], v[226:229], 0
	v_mfma_f32_16x16x32_bf16 v[116:119], v[186:189], v[202:205], v[116:119]
	v_mfma_f32_16x16x32_bf16 v[108:111], v[194:197], v[202:205], v[108:111]
	v_mfma_f32_16x16x32_bf16 v[96:99], v[186:189], v[210:213], v[96:99]
	v_mfma_f32_16x16x32_bf16 v[88:91], v[194:197], v[210:213], v[88:91]
	v_mfma_f32_16x16x32_bf16 v[80:83], v[186:189], v[218:221], v[80:83]
	v_mfma_f32_16x16x32_bf16 v[72:75], v[194:197], v[218:221], v[72:75]
	v_mfma_f32_16x16x32_bf16 v[68:71], v[186:189], v[230:233], v[68:71]
	v_mfma_f32_16x16x32_bf16 v[64:67], v[194:197], v[230:233], v[64:67]
	s_setprio 0
	s_barrier
	s_add_i32 s90, s85, s39
	v_lshl_add_u64 v[174:175], s[10:11], 0, v[130:131]
	s_mov_b32 m0, s90
	ds_read_b128 v[198:201], v164 offset:16384
	ds_read_b128 v[202:205], v164 offset:17408
	ds_read_b128 v[206:209], v164 offset:18432
	ds_read_b128 v[210:213], v164 offset:19456
	ds_read_b128 v[214:217], v164 offset:20480
	ds_read_b128 v[218:221], v164 offset:21504
	ds_read_b128 v[226:229], v164 offset:22528
	ds_read_b128 v[230:233], v164 offset:23552
	global_load_lds_dwordx4 v[174:175], off
	s_add_i32 m0, s90, 0x2000
	s_add_u32 s90, s10, 0x40000
	v_lshl_add_u64 v[222:223], s[10:11], 0, v[134:135]
	s_addc_u32 s91, s11, 0
	s_add_i32 s92, s86, s39
	global_load_lds_dwordx4 v[222:223], off
	v_lshl_add_u64 v[234:235], s[90:91], 0, v[130:131]
	s_mov_b32 m0, s92
	v_lshl_add_u64 v[236:237], s[12:13], 0, v[132:133]
	global_load_lds_dwordx4 v[234:235], off
	v_lshl_add_u64 v[234:235], s[90:91], 0, v[134:135]
	s_add_i32 m0, s92, 0x2000
	s_nop 0
	global_load_lds_dwordx4 v[234:235], off
	v_lshl_add_u64 v[234:235], s[12:13], 0, v[128:129]
	s_mov_b32 m0, s43
	s_nop 0
	global_load_lds_dwordx4 v[234:235], off
	s_mov_b32 m0, s53
	s_nop 0
	global_load_lds_dwordx4 v[236:237], off
	s_waitcnt vmcnt(8)
	s_waitcnt lgkmcnt(0)
	s_barrier
; #define PG8_STAGE(bufoff, gbase, voff) do { _Pragma("unroll") for (int _i = 0; _i < 2; ++_i) \
;         __builtin_amdgcn_global_load_lds((const unsigned*)((const char*)(gbase) + (voff)[_i]), (LAS unsigned*)(lds + (bufoff) + ldsw + _i * 8192), 16, 0, 0); } while (0)
; #define PG8_LDA(dst, b, h) do { _Pragma("unroll") for (int m = 0; m < 4; ++m) _Pragma("unroll") for (int k = 0; k < 2; ++k) dst[m][k] = *(const LAS bf16x8*)(lds + PG8_SA(b, h) + aoff + m * 2048 + k * 1024); } while (0)
; #define PG8_LDB(dst, b, h) do { _Pragma("unroll") for (int n = 0; n < 2; ++n) _Pragma("unroll") for (int k = 0; k < 2; ++k) dst[n][k] = *(const LAS bf16x8*)(lds + PG8_SB(b, h) + boff + n * 2048 + k * 1024); } while (0)
; #define PG8_MMA(ai, bj, At, Bt) do { __builtin_amdgcn_s_setprio(1); _Pragma("unroll") for (int m = 0; m < 4; ++m) _Pragma("unroll") for (int n = 0; n < 2; ++n) _Pragma("unroll") for (int k = 0; k < 2; ++k) \
;         acc[ai][bj][m][n] = __builtin_amdgcn_mfma_f32_16x16x32_bf16(Bt[n][k], At[m][k], acc[ai][bj][m][n], 0, 0, 0); __builtin_amdgcn_s_setprio(0); } while (0)
; #define PG8_WAIT_V(n) asm volatile("s_waitcnt vmcnt(" #n ")" ::: "memory")
; #define PG8_WAIT_L(n) asm volatile("s_waitcnt lgkmcnt(" #n ")" ::: "memory")
; #define PG8_BAR __builtin_amdgcn_s_barrier()
; #define PG8_SCHED __builtin_amdgcn_sched_barrier(0)
; template <class Epi>
; __device__ __forceinline__ void gemm_phase(LAS unsigned char* lds, const Gemm g, const StaticOrder& S, const Epi& E) {
;     ...
;             PG8_WAIT_V(8); PG8_WAIT_L(0); PG8_BAR; PG8_MMA(1, 0, At, B0); PG8_MMA(1, 1, At, B1); PG8_BAR; PG8_SCHED;
;             PG8_LDB(B0, 1, 0); PG8_LDB(B1, 1, 1); PG8_SCHED; PG8_LDA(At, 1, 0); PG8_STAGE(PG8_SA(0, 1), a2 + hstepA, voffA);
;             PG8_WAIT_V(8); PG8_WAIT_L(0); PG8_BAR; PG8_MMA(0, 0, At, B0); PG8_MMA(0, 1, At, B1); PG8_BAR; PG8_SCHED;
;             PG8_LDA(At, 1, 1); PG8_STAGE(PG8_SB(1, 0), b3, voffB); PG8_STAGE(PG8_SB(1, 1), b3 + hstepB, voffB); PG8_STAGE(PG8_SA(1, 0), a3, voffA);
;             PG8_WAIT_V(8); PG8_WAIT_L(0); PG8_BAR; PG8_MMA(1, 0, At, B0); PG8_MMA(1, 1, At, B1); PG8_BAR; PG8_SCHED;
	s_setprio 1
	s_waitcnt lgkmcnt(0)
	v_mfma_f32_16x16x32_bf16 v[60:63], v[146:149], v[198:201], 0
	v_mfma_f32_16x16x32_bf16 v[56:59], v[170:173], v[198:201], 0
	v_mfma_f32_16x16x32_bf16 v[52:55], v[146:149], v[206:209], 0
	v_mfma_f32_16x16x32_bf16 v[44:47], v[170:173], v[206:209], 0
	v_mfma_f32_16x16x32_bf16 v[36:39], v[146:149], v[214:217], 0
	v_mfma_f32_16x16x32_bf16 v[28:31], v[170:173], v[214:217], 0
	v_mfma_f32_16x16x32_bf16 v[20:23], v[146:149], v[226:229], 0
	v_mfma_f32_16x16x32_bf16 v[12:15], v[170:173], v[226:229], 0
	v_mfma_f32_16x16x32_bf16 v[60:63], v[166:169], v[202:205], v[60:63]
	v_mfma_f32_16x16x32_bf16 v[56:59], v[178:181], v[202:205], v[56:59]
	v_mfma_f32_16x16x32_bf16 v[52:55], v[166:169], v[210:213], v[52:55]
	v_mfma_f32_16x16x32_bf16 v[44:47], v[178:181], v[210:213], v[44:47]
	v_mfma_f32_16x16x32_bf16 v[36:39], v[166:169], v[218:221], v[36:39]
	v_mfma_f32_16x16x32_bf16 v[28:31], v[178:181], v[218:221], v[28:31]
	v_mfma_f32_16x16x32_bf16 v[20:23], v[166:169], v[230:233], v[20:23]
	v_mfma_f32_16x16x32_bf16 v[12:15], v[178:181], v[230:233], v[12:15]
	s_setprio 0
	s_setprio 1
	v_mfma_f32_16x16x32_bf16 v[48:51], v[182:185], v[198:201], 0
	v_mfma_f32_16x16x32_bf16 v[40:43], v[190:193], v[198:201], 0
	v_mfma_f32_16x16x32_bf16 v[32:35], v[182:185], v[206:209], 0
	v_mfma_f32_16x16x32_bf16 v[24:27], v[190:193], v[206:209], 0
	v_mfma_f32_16x16x32_bf16 v[16:19], v[182:185], v[214:217], 0
	v_mfma_f32_16x16x32_bf16 v[8:11], v[190:193], v[214:217], 0
	v_mfma_f32_16x16x32_bf16 v[4:7], v[182:185], v[226:229], 0
	v_mfma_f32_16x16x32_bf16 v[0:3], v[190:193], v[226:229], 0
	v_mfma_f32_16x16x32_bf16 v[48:51], v[186:189], v[202:205], v[48:51]
	v_mfma_f32_16x16x32_bf16 v[40:43], v[194:197], v[202:205], v[40:43]
	v_mfma_f32_16x16x32_bf16 v[32:35], v[186:189], v[210:213], v[32:35]
	v_mfma_f32_16x16x32_bf16 v[24:27], v[194:197], v[210:213], v[24:27]
	v_mfma_f32_16x16x32_bf16 v[16:19], v[186:189], v[218:221], v[16:19]
	v_mfma_f32_16x16x32_bf16 v[8:11], v[194:197], v[218:221], v[8:11]
	v_mfma_f32_16x16x32_bf16 v[4:7], v[186:189], v[230:233], v[4:7]
	v_mfma_f32_16x16x32_bf16 v[0:3], v[194:197], v[230:233], v[0:3]
	s_setprio 0
	s_barrier
	s_add_i32 s90, 0, 0x18000
	v_add_u32_e32 v136, s90, v161
	s_add_i32 s91, 0, 0x1c000
	ds_read_b128 v[146:149], v136
	ds_read_b128 v[166:169], v136 offset:1024
	ds_read_b128 v[170:173], v136 offset:2048
	ds_read_b128 v[178:181], v136 offset:3072
	v_add_u32_e32 v136, s91, v161
	ds_read_b128 v[182:185], v136
	ds_read_b128 v[186:189], v136 offset:1024
	ds_read_b128 v[190:193], v136 offset:2048
	ds_read_b128 v[194:197], v136 offset:3072
	s_add_u32 s12, s12, 0x40000
	s_addc_u32 s13, s13, 0
	s_mov_b32 m0, s55
	v_lshl_add_u64 v[238:239], s[12:13], 0, v[128:129]
	ds_read_b128 v[198:201], v164 offset:32768
	ds_read_b128 v[202:205], v164 offset:33792
	ds_read_b128 v[206:209], v164 offset:34816
	ds_read_b128 v[210:213], v164 offset:35840
	ds_read_b128 v[214:217], v164 offset:36864
	ds_read_b128 v[218:221], v164 offset:37888
	ds_read_b128 v[226:229], v164 offset:38912
	ds_read_b128 v[230:233], v164 offset:39936
	global_load_lds_dwordx4 v[238:239], off
	v_lshl_add_u64 v[238:239], s[12:13], 0, v[132:133]
	s_mov_b32 m0, s57
	s_nop 0
	global_load_lds_dwordx4 v[238:239], off
	s_waitcnt vmcnt(8)
	s_waitcnt lgkmcnt(0)
	s_barrier
	s_setprio 1
	s_waitcnt lgkmcnt(0)
	v_mfma_f32_16x16x32_bf16 v[124:127], v[146:149], v[198:201], v[124:127]
	v_mfma_f32_16x16x32_bf16 v[120:123], v[170:173], v[198:201], v[120:123]
	v_mfma_f32_16x16x32_bf16 v[112:115], v[146:149], v[206:209], v[112:115]
	v_mfma_f32_16x16x32_bf16 v[104:107], v[170:173], v[206:209], v[104:107]
	v_mfma_f32_16x16x32_bf16 v[100:103], v[146:149], v[214:217], v[100:103]
	v_mfma_f32_16x16x32_bf16 v[92:95], v[170:173], v[214:217], v[92:95]
	v_mfma_f32_16x16x32_bf16 v[84:87], v[146:149], v[226:229], v[84:87]
	v_mfma_f32_16x16x32_bf16 v[76:79], v[170:173], v[226:229], v[76:79]
	v_mfma_f32_16x16x32_bf16 v[124:127], v[166:169], v[202:205], v[124:127]
	v_mfma_f32_16x16x32_bf16 v[120:123], v[178:181], v[202:205], v[120:123]
	v_mfma_f32_16x16x32_bf16 v[112:115], v[166:169], v[210:213], v[112:115]
	v_mfma_f32_16x16x32_bf16 v[104:107], v[178:181], v[210:213], v[104:107]
	v_mfma_f32_16x16x32_bf16 v[100:103], v[166:169], v[218:221], v[100:103]
	v_mfma_f32_16x16x32_bf16 v[92:95], v[178:181], v[218:221], v[92:95]
	v_mfma_f32_16x16x32_bf16 v[84:87], v[166:169], v[230:233], v[84:87]
	v_mfma_f32_16x16x32_bf16 v[76:79], v[178:181], v[230:233], v[76:79]
	s_setprio 0
	s_setprio 1
	v_mfma_f32_16x16x32_bf16 v[116:119], v[182:185], v[198:201], v[116:119]
	v_mfma_f32_16x16x32_bf16 v[108:111], v[190:193], v[198:201], v[108:111]
	v_mfma_f32_16x16x32_bf16 v[96:99], v[182:185], v[206:209], v[96:99]
	v_mfma_f32_16x16x32_bf16 v[88:91], v[190:193], v[206:209], v[88:91]
	v_mfma_f32_16x16x32_bf16 v[80:83], v[182:185], v[214:217], v[80:83]
	v_mfma_f32_16x16x32_bf16 v[72:75], v[190:193], v[214:217], v[72:75]
	v_mfma_f32_16x16x32_bf16 v[68:71], v[182:185], v[226:229], v[68:71]
	v_mfma_f32_16x16x32_bf16 v[64:67], v[190:193], v[226:229], v[64:67]
	v_mfma_f32_16x16x32_bf16 v[116:119], v[186:189], v[202:205], v[116:119]
	v_mfma_f32_16x16x32_bf16 v[108:111], v[194:197], v[202:205], v[108:111]
	v_mfma_f32_16x16x32_bf16 v[96:99], v[186:189], v[210:213], v[96:99]
	v_mfma_f32_16x16x32_bf16 v[88:91], v[194:197], v[210:213], v[88:91]
	v_mfma_f32_16x16x32_bf16 v[80:83], v[186:189], v[218:221], v[80:83]
	v_mfma_f32_16x16x32_bf16 v[72:75], v[194:197], v[218:221], v[72:75]
	v_mfma_f32_16x16x32_bf16 v[68:71], v[186:189], v[230:233], v[68:71]
	v_mfma_f32_16x16x32_bf16 v[64:67], v[194:197], v[230:233], v[64:67]
	s_setprio 0
	s_barrier
; #define PG8_STAGE(bufoff, gbase, voff) do { _Pragma("unroll") for (int _i = 0; _i < 2; ++_i) \
;         __builtin_amdgcn_global_load_lds((const unsigned*)((const char*)(gbase) + (voff)[_i]), (LAS unsigned*)(lds + (bufoff) + ldsw + _i * 8192), 16, 0, 0); } while (0)
; #define PG8_LDA(dst, b, h) do { _Pragma("unroll") for (int m = 0; m < 4; ++m) _Pragma("unroll") for (int k = 0; k < 2; ++k) dst[m][k] = *(const LAS bf16x8*)(lds + PG8_SA(b, h) + aoff + m * 2048 + k * 1024); } while (0)
; #define PG8_MMA(ai, bj, At, Bt) do { __builtin_amdgcn_s_setprio(1); _Pragma("unroll") for (int m = 0; m < 4; ++m) _Pragma("unroll") for (int n = 0; n < 2; ++n) _Pragma("unroll") for (int k = 0; k < 2; ++k) \
;         acc[ai][bj][m][n] = __builtin_amdgcn_mfma_f32_16x16x32_bf16(Bt[n][k], At[m][k], acc[ai][bj][m][n], 0, 0, 0); __builtin_amdgcn_s_setprio(0); } while (0)
; #define PG8_WAIT_V(n) asm volatile("s_waitcnt vmcnt(" #n ")" ::: "memory")
; #define PG8_WAIT_L(n) asm volatile("s_waitcnt lgkmcnt(" #n ")" ::: "memory")
; #define PG8_BAR __builtin_amdgcn_s_barrier()
; #define PG8_SCHED __builtin_amdgcn_sched_barrier(0)
; template <class Epi>
; __device__ __forceinline__ void gemm_phase(LAS unsigned char* lds, const Gemm g, const StaticOrder& S, const Epi& E) {
;     ...
;             PG8_LDA(At, 1, 1); PG8_STAGE(PG8_SB(1, 0), b3, voffB); PG8_STAGE(PG8_SB(1, 1), b3 + hstepB, voffB); PG8_STAGE(PG8_SA(1, 0), a3, voffA);
;             PG8_WAIT_V(8); PG8_WAIT_L(0); PG8_BAR; PG8_MMA(1, 0, At, B0); PG8_MMA(1, 1, At, B1); PG8_BAR; PG8_SCHED;
;         }
	s_add_i32 s12, s90, s39
	v_lshl_add_u64 v[174:175], v[174:175], 0, s[30:31]
	s_mov_b32 m0, s12
	ds_read_b128 v[198:201], v164 offset:49152
	ds_read_b128 v[202:205], v164 offset:50176
	ds_read_b128 v[206:209], v164 offset:51200
	ds_read_b128 v[210:213], v164 offset:52224
	ds_read_b128 v[214:217], v164 offset:53248
	ds_read_b128 v[218:221], v164 offset:54272
	ds_read_b128 v[226:229], v164 offset:55296
	ds_read_b128 v[230:233], v164 offset:56320
	global_load_lds_dwordx4 v[174:175], off
	s_add_i32 m0, s12, 0x2000
	s_add_u32 s10, s10, 0x40080
	v_lshl_add_u64 v[174:175], v[222:223], 0, s[30:31]
	s_addc_u32 s11, s11, 0
	s_add_i32 s12, s91, s39
	global_load_lds_dwordx4 v[174:175], off
	v_lshl_add_u64 v[174:175], s[10:11], 0, v[130:131]
	s_mov_b32 m0, s12
	s_nop 0
	global_load_lds_dwordx4 v[174:175], off
	v_lshl_add_u64 v[174:175], s[10:11], 0, v[134:135]
	s_add_i32 m0, s12, 0x2000
	s_nop 0
	global_load_lds_dwordx4 v[174:175], off
	v_lshl_add_u64 v[174:175], v[234:235], 0, s[30:31]
	s_mov_b32 m0, s79
	s_nop 0
	global_load_lds_dwordx4 v[174:175], off
	v_lshl_add_u64 v[174:175], v[236:237], 0, s[30:31]
	s_mov_b32 m0, s80
	s_nop 0
	global_load_lds_dwordx4 v[174:175], off
	s_waitcnt vmcnt(8)
	s_waitcnt lgkmcnt(0)
	s_barrier
	s_setprio 1
	s_waitcnt lgkmcnt(0)
	v_mfma_f32_16x16x32_bf16 v[60:63], v[146:149], v[198:201], v[60:63]
	v_mfma_f32_16x16x32_bf16 v[56:59], v[170:173], v[198:201], v[56:59]
	v_mfma_f32_16x16x32_bf16 v[52:55], v[146:149], v[206:209], v[52:55]
	v_mfma_f32_16x16x32_bf16 v[44:47], v[170:173], v[206:209], v[44:47]
	v_mfma_f32_16x16x32_bf16 v[36:39], v[146:149], v[214:217], v[36:39]
	v_mfma_f32_16x16x32_bf16 v[28:31], v[170:173], v[214:217], v[28:31]
	v_mfma_f32_16x16x32_bf16 v[20:23], v[146:149], v[226:229], v[20:23]
	v_mfma_f32_16x16x32_bf16 v[12:15], v[170:173], v[226:229], v[12:15]
	v_mfma_f32_16x16x32_bf16 v[60:63], v[166:169], v[202:205], v[60:63]
	v_mfma_f32_16x16x32_bf16 v[56:59], v[178:181], v[202:205], v[56:59]
	v_mfma_f32_16x16x32_bf16 v[52:55], v[166:169], v[210:213], v[52:55]
	v_mfma_f32_16x16x32_bf16 v[44:47], v[178:181], v[210:213], v[44:47]
	v_mfma_f32_16x16x32_bf16 v[36:39], v[166:169], v[218:221], v[36:39]
	v_mfma_f32_16x16x32_bf16 v[28:31], v[178:181], v[218:221], v[28:31]
	v_mfma_f32_16x16x32_bf16 v[20:23], v[166:169], v[230:233], v[20:23]
	v_mfma_f32_16x16x32_bf16 v[12:15], v[178:181], v[230:233], v[12:15]
	s_setprio 0
	s_setprio 1
	v_mfma_f32_16x16x32_bf16 v[48:51], v[182:185], v[198:201], v[48:51]
	v_mfma_f32_16x16x32_bf16 v[40:43], v[190:193], v[198:201], v[40:43]
	v_mfma_f32_16x16x32_bf16 v[32:35], v[182:185], v[206:209], v[32:35]
	v_mfma_f32_16x16x32_bf16 v[24:27], v[190:193], v[206:209], v[24:27]
	v_mfma_f32_16x16x32_bf16 v[16:19], v[182:185], v[214:217], v[16:19]
	v_mfma_f32_16x16x32_bf16 v[8:11], v[190:193], v[214:217], v[8:11]
	v_mfma_f32_16x16x32_bf16 v[4:7], v[182:185], v[226:229], v[4:7]
	v_mfma_f32_16x16x32_bf16 v[0:3], v[190:193], v[226:229], v[0:3]
	v_mfma_f32_16x16x32_bf16 v[48:51], v[186:189], v[202:205], v[48:51]
	v_mfma_f32_16x16x32_bf16 v[40:43], v[194:197], v[202:205], v[40:43]
	v_mfma_f32_16x16x32_bf16 v[32:35], v[186:189], v[210:213], v[32:35]
	v_mfma_f32_16x16x32_bf16 v[24:27], v[194:197], v[210:213], v[24:27]
	v_mfma_f32_16x16x32_bf16 v[16:19], v[186:189], v[218:221], v[16:19]
	v_mfma_f32_16x16x32_bf16 v[8:11], v[194:197], v[218:221], v[8:11]
	v_mfma_f32_16x16x32_bf16 v[4:7], v[186:189], v[230:233], v[4:7]
	v_mfma_f32_16x16x32_bf16 v[0:3], v[194:197], v[230:233], v[0:3]
	s_setprio 0
	s_barrier
	s_add_i32 s89, s89, 2
	s_add_u32 s8, s8, 0x100
	s_addc_u32 s9, s9, 0
	s_add_u32 s76, s76, 0x100
	s_addc_u32 s77, s77, 0
	s_cmp_gt_u32 s89, 13

; #define PG8_STAGE(bufoff, gbase, voff) do { _Pragma("unroll") for (int _i = 0; _i < 2; ++_i) \
;         __builtin_amdgcn_global_load_lds((const unsigned*)((const char*)(gbase) + (voff)[_i]), (LAS unsigned*)(lds + (bufoff) + ldsw + _i * 8192), 16, 0, 0); } while (0)
; #define PG8_LDA(dst, b, h) do { _Pragma("unroll") for (int m = 0; m < 4; ++m) _Pragma("unroll") for (int k = 0; k < 2; ++k) dst[m][k] = *(const LAS bf16x8*)(lds + PG8_SA(b, h) + aoff + m * 2048 + k * 1024); } while (0)
; #define PG8_LDB(dst, b, h) do { _Pragma("unroll") for (int n = 0; n < 2; ++n) _Pragma("unroll") for (int k = 0; k < 2; ++k) dst[n][k] = *(const LAS bf16x8*)(lds + PG8_SB(b, h) + boff + n * 2048 + k * 1024); } while (0)
; #define PG8_MMA(ai, bj, At, Bt) do { __builtin_amdgcn_s_setprio(1); _Pragma("unroll") for (int m = 0; m < 4; ++m) _Pragma("unroll") for (int n = 0; n < 2; ++n) _Pragma("unroll") for (int k = 0; k < 2; ++k) \
;         acc[ai][bj][m][n] = __builtin_amdgcn_mfma_f32_16x16x32_bf16(Bt[n][k], At[m][k], acc[ai][bj][m][n], 0, 0, 0); __builtin_amdgcn_s_setprio(0); } while (0)
; #define PG8_BAR __builtin_amdgcn_s_barrier()
; template <class Epi>
; __device__ __forceinline__ void gemm_phase(LAS unsigned char* lds, const Gemm g, const StaticOrder& S, const Epi& E) {
;     ...
;         const bool has_next = S.next(ui + 1, nxt);
;         const char* nA = has_next ? (const char*)g.A + (size_t)nxt.pm * tstepA : cA; const char* nB = has_next ? (const char*)g.Bt + (size_t)nxt.pn * tstepB : cB;
; #pragma nounroll
;         for (int t = 0; t < nt; t += 2) {
;             const bool last = (t == nt - 2);
;             const char* a1 = cA + (size_t)(t + 1) * kstep;
;             const char* a2 = last ? nA : cA + (size_t)(t + 2) * kstep; const char* b2 = last ? nB : cB + (size_t)(t + 2) * kstep;
;             const char* a3 = a2 + kstep; const char* b3 = b2 + kstep;
;             PG8_LDB(B0, 0, 0); PG8_LDB(B1, 0, 1); PG8_SCHED; PG8_LDA(At, 0, 0); PG8_STAGE(PG8_SA(1, 1), a1 + hstepA, voffA);
;             PG8_WAIT_V(8); PG8_WAIT_L(0); PG8_BAR; PG8_MMA(0, 0, At, B0); PG8_MMA(0, 1, At, B1); PG8_BAR; PG8_SCHED;
;             PG8_LDA(At, 0, 1); PG8_STAGE(PG8_SB(0, 0), b2, voffB); PG8_STAGE(PG8_SB(0, 1), b2 + hstepB, voffB); PG8_STAGE(PG8_SA(0, 0), a2, voffA);
;             PG8_WAIT_V(8); PG8_WAIT_L(0); PG8_BAR; PG8_MMA(1, 0, At, B0); PG8_MMA(1, 1, At, B1); PG8_BAR; PG8_SCHED;
.LBB0_791:
	s_add_u32 s0, s0, 0xb0080
	s_addc_u32 s1, s1, 0
	s_add_u32 s75, s34, 0x100
	s_addc_u32 s76, s35, 0
	s_mov_b32 s77, -2
	s_waitcnt lgkmcnt(0)
	s_nop 0
	ds_read_b128 v[128:131], v182
	ds_read_b128 v[132:135], v182 offset:1024
	ds_read_b128 v[136:139], v182 offset:2048
	ds_read_b128 v[140:143], v182 offset:3072
	ds_read_b128 v[160:163], v183
	ds_read_b128 v[164:167], v183 offset:1024
	ds_read_b128 v[168:171], v183 offset:2048
	ds_read_b128 v[172:175], v183 offset:3072
	s_add_u32 s34, s0, 0xfff50080
	s_addc_u32 s35, s1, -1
	s_cmp_eq_u32 s77, 40
	s_cselect_b32 s39, s7, s35
	s_cselect_b32 s38, s6, s34
	s_cselect_b32 s35, s23, s76
	s_cselect_b32 s34, s22, s75
	v_lshl_add_u64 v[178:179], s[0:1], 0, v[152:153]
	s_add_i32 m0, s43, 0xc000
	ds_read_b128 v[186:189], v184
	ds_read_b128 v[190:193], v184 offset:1024
	ds_read_b128 v[194:197], v184 offset:2048
	ds_read_b128 v[198:201], v184 offset:3072
	ds_read_b128 v[202:205], v184 offset:4096
	ds_read_b128 v[206:209], v184 offset:5120
	ds_read_b128 v[210:213], v184 offset:6144
	ds_read_b128 v[214:217], v184 offset:7168
	global_load_lds_dwordx4 v[178:179], off
	v_lshl_add_u64 v[178:179], s[0:1], 0, v[154:155]
	s_add_i32 m0, s43, 0xe000
	s_nop 0
	global_load_lds_dwordx4 v[178:179], off
	s_waitcnt vmcnt(8)
	s_waitcnt lgkmcnt(0)
	s_barrier
	s_setprio 1
	s_waitcnt lgkmcnt(0)
	v_mfma_f32_16x16x32_bf16 v[124:127], v[128:131], v[186:189], 0
	v_mfma_f32_16x16x32_bf16 v[120:123], v[136:139], v[186:189], 0
	v_mfma_f32_16x16x32_bf16 v[108:111], v[128:131], v[194:197], 0
	v_mfma_f32_16x16x32_bf16 v[104:107], v[136:139], v[194:197], 0
	v_mfma_f32_16x16x32_bf16 v[92:95], v[128:131], v[202:205], 0
	v_mfma_f32_16x16x32_bf16 v[88:91], v[136:139], v[202:205], 0
	v_mfma_f32_16x16x32_bf16 v[76:79], v[128:131], v[210:213], 0
	v_mfma_f32_16x16x32_bf16 v[72:75], v[136:139], v[210:213], 0
	v_mfma_f32_16x16x32_bf16 v[124:127], v[132:135], v[190:193], v[124:127]
	v_mfma_f32_16x16x32_bf16 v[120:123], v[140:143], v[190:193], v[120:123]
	v_mfma_f32_16x16x32_bf16 v[108:111], v[132:135], v[198:201], v[108:111]
	v_mfma_f32_16x16x32_bf16 v[104:107], v[140:143], v[198:201], v[104:107]
	v_mfma_f32_16x16x32_bf16 v[92:95], v[132:135], v[206:209], v[92:95]
	v_mfma_f32_16x16x32_bf16 v[88:91], v[140:143], v[206:209], v[88:91]
	v_mfma_f32_16x16x32_bf16 v[76:79], v[132:135], v[214:217], v[76:79]
	v_mfma_f32_16x16x32_bf16 v[72:75], v[140:143], v[214:217], v[72:75]
	s_setprio 0
	s_setprio 1
	v_mfma_f32_16x16x32_bf16 v[116:119], v[160:163], v[186:189], 0
	v_mfma_f32_16x16x32_bf16 v[112:115], v[168:171], v[186:189], 0
	v_mfma_f32_16x16x32_bf16 v[100:103], v[160:163], v[194:197], 0
	v_mfma_f32_16x16x32_bf16 v[96:99], v[168:171], v[194:197], 0
	v_mfma_f32_16x16x32_bf16 v[84:87], v[160:163], v[202:205], 0
	v_mfma_f32_16x16x32_bf16 v[80:83], v[168:171], v[202:205], 0
	v_mfma_f32_16x16x32_bf16 v[68:71], v[160:163], v[210:213], 0
	v_mfma_f32_16x16x32_bf16 v[64:67], v[168:171], v[210:213], 0
	v_mfma_f32_16x16x32_bf16 v[116:119], v[164:167], v[190:193], v[116:119]
	v_mfma_f32_16x16x32_bf16 v[112:115], v[172:175], v[190:193], v[112:115]
	v_mfma_f32_16x16x32_bf16 v[100:103], v[164:167], v[198:201], v[100:103]
	v_mfma_f32_16x16x32_bf16 v[96:99], v[172:175], v[198:201], v[96:99]
	v_mfma_f32_16x16x32_bf16 v[84:87], v[164:167], v[206:209], v[84:87]
	v_mfma_f32_16x16x32_bf16 v[80:83], v[172:175], v[206:209], v[80:83]
	v_mfma_f32_16x16x32_bf16 v[68:71], v[164:167], v[214:217], v[68:71]
	v_mfma_f32_16x16x32_bf16 v[64:67], v[172:175], v[214:217], v[64:67]
	s_setprio 0
	s_barrier
	s_add_i32 s78, s69, s42
	v_lshl_add_u64 v[178:179], s[34:35], 0, v[146:147]
	s_mov_b32 m0, s78
	ds_read_b128 v[186:189], v184 offset:16384
	ds_read_b128 v[190:193], v184 offset:17408
	ds_read_b128 v[194:197], v184 offset:18432
	ds_read_b128 v[198:201], v184 offset:19456
	ds_read_b128 v[202:205], v184 offset:20480
	ds_read_b128 v[206:209], v184 offset:21504
	ds_read_b128 v[210:213], v184 offset:22528
	ds_read_b128 v[214:217], v184 offset:23552
	global_load_lds_dwordx4 v[178:179], off
	s_add_i32 m0, s78, 0x2000
	s_add_u32 s78, s34, 0xb0000
	v_lshl_add_u64 v[218:219], s[34:35], 0, v[150:151]
	s_addc_u32 s79, s35, 0
	s_add_i32 s80, s70, s42
	global_load_lds_dwordx4 v[218:219], off
	v_lshl_add_u64 v[220:221], s[78:79], 0, v[146:147]
	s_mov_b32 m0, s80
	v_lshl_add_u64 v[222:223], s[38:39], 0, v[148:149]
	global_load_lds_dwordx4 v[220:221], off
	v_lshl_add_u64 v[220:221], s[78:79], 0, v[150:151]
	s_add_i32 m0, s80, 0x2000
	s_nop 0
	global_load_lds_dwordx4 v[220:221], off
	v_lshl_add_u64 v[220:221], s[38:39], 0, v[144:145]
	s_mov_b32 m0, s43
	s_nop 0
	global_load_lds_dwordx4 v[220:221], off
	s_mov_b32 m0, s52
	s_nop 0
	global_load_lds_dwordx4 v[222:223], off
	s_waitcnt vmcnt(8)
	s_waitcnt lgkmcnt(0)
	s_barrier
; #define PG8_STAGE(bufoff, gbase, voff) do { _Pragma("unroll") for (int _i = 0; _i < 2; ++_i) \
;         __builtin_amdgcn_global_load_lds((const unsigned*)((const char*)(gbase) + (voff)[_i]), (LAS unsigned*)(lds + (bufoff) + ldsw + _i * 8192), 16, 0, 0); } while (0)
; #define PG8_LDA(dst, b, h) do { _Pragma("unroll") for (int m = 0; m < 4; ++m) _Pragma("unroll") for (int k = 0; k < 2; ++k) dst[m][k] = *(const LAS bf16x8*)(lds + PG8_SA(b, h) + aoff + m * 2048 + k * 1024); } while (0)
; #define PG8_LDB(dst, b, h) do { _Pragma("unroll") for (int n = 0; n < 2; ++n) _Pragma("unroll") for (int k = 0; k < 2; ++k) dst[n][k] = *(const LAS bf16x8*)(lds + PG8_SB(b, h) + boff + n * 2048 + k * 1024); } while (0)
; #define PG8_MMA(ai, bj, At, Bt) do { __builtin_amdgcn_s_setprio(1); _Pragma("unroll") for (int m = 0; m < 4; ++m) _Pragma("unroll") for (int n = 0; n < 2; ++n) _Pragma("unroll") for (int k = 0; k < 2; ++k) \
;         acc[ai][bj][m][n] = __builtin_amdgcn_mfma_f32_16x16x32_bf16(Bt[n][k], At[m][k], acc[ai][bj][m][n], 0, 0, 0); __builtin_amdgcn_s_setprio(0); } while (0)
; #define PG8_WAIT_V(n) asm volatile("s_waitcnt vmcnt(" #n ")" ::: "memory")
; #define PG8_WAIT_L(n) asm volatile("s_waitcnt lgkmcnt(" #n ")" ::: "memory")
; #define PG8_BAR __builtin_amdgcn_s_barrier()
; #define PG8_SCHED __builtin_amdgcn_sched_barrier(0)
; template <class Epi>
; __device__ __forceinline__ void gemm_phase(LAS unsigned char* lds, const Gemm g, const StaticOrder& S, const Epi& E) {
;     ...
;             PG8_WAIT_V(8); PG8_WAIT_L(0); PG8_BAR; PG8_MMA(1, 0, At, B0); PG8_MMA(1, 1, At, B1); PG8_BAR; PG8_SCHED;
;             PG8_LDB(B0, 1, 0); PG8_LDB(B1, 1, 1); PG8_SCHED; PG8_LDA(At, 1, 0); PG8_STAGE(PG8_SA(0, 1), a2 + hstepA, voffA);
;             PG8_WAIT_V(8); PG8_WAIT_L(0); PG8_BAR; PG8_MMA(0, 0, At, B0); PG8_MMA(0, 1, At, B1); PG8_BAR; PG8_SCHED;
;             PG8_LDA(At, 1, 1); PG8_STAGE(PG8_SB(1, 0), b3, voffB); PG8_STAGE(PG8_SB(1, 1), b3 + hstepB, voffB); PG8_STAGE(PG8_SA(1, 0), a3, voffA);
;             PG8_WAIT_V(8); PG8_WAIT_L(0); PG8_BAR; PG8_MMA(1, 0, At, B0); PG8_MMA(1, 1, At, B1); PG8_BAR; PG8_SCHED;
	s_setprio 1
	s_waitcnt lgkmcnt(0)
	v_mfma_f32_16x16x32_bf16 v[60:63], v[128:131], v[186:189], 0
	v_mfma_f32_16x16x32_bf16 v[56:59], v[136:139], v[186:189], 0
	v_mfma_f32_16x16x32_bf16 v[44:47], v[128:131], v[194:197], 0
	v_mfma_f32_16x16x32_bf16 v[40:43], v[136:139], v[194:197], 0
	v_mfma_f32_16x16x32_bf16 v[28:31], v[128:131], v[202:205], 0
	v_mfma_f32_16x16x32_bf16 v[24:27], v[136:139], v[202:205], 0
	v_mfma_f32_16x16x32_bf16 v[12:15], v[128:131], v[210:213], 0
	v_mfma_f32_16x16x32_bf16 v[8:11], v[136:139], v[210:213], 0
	v_mfma_f32_16x16x32_bf16 v[60:63], v[132:135], v[190:193], v[60:63]
	v_mfma_f32_16x16x32_bf16 v[56:59], v[140:143], v[190:193], v[56:59]
	v_mfma_f32_16x16x32_bf16 v[44:47], v[132:135], v[198:201], v[44:47]
	v_mfma_f32_16x16x32_bf16 v[40:43], v[140:143], v[198:201], v[40:43]
	v_mfma_f32_16x16x32_bf16 v[28:31], v[132:135], v[206:209], v[28:31]
	v_mfma_f32_16x16x32_bf16 v[24:27], v[140:143], v[206:209], v[24:27]
	v_mfma_f32_16x16x32_bf16 v[12:15], v[132:135], v[214:217], v[12:15]
	v_mfma_f32_16x16x32_bf16 v[8:11], v[140:143], v[214:217], v[8:11]
	s_setprio 0
	s_setprio 1
	v_mfma_f32_16x16x32_bf16 v[52:55], v[160:163], v[186:189], 0
	v_mfma_f32_16x16x32_bf16 v[48:51], v[168:171], v[186:189], 0
	v_mfma_f32_16x16x32_bf16 v[36:39], v[160:163], v[194:197], 0
	v_mfma_f32_16x16x32_bf16 v[32:35], v[168:171], v[194:197], 0
	v_mfma_f32_16x16x32_bf16 v[20:23], v[160:163], v[202:205], 0
	v_mfma_f32_16x16x32_bf16 v[16:19], v[168:171], v[202:205], 0
	v_mfma_f32_16x16x32_bf16 v[4:7], v[160:163], v[210:213], 0
	v_mfma_f32_16x16x32_bf16 v[0:3], v[168:171], v[210:213], 0
	v_mfma_f32_16x16x32_bf16 v[52:55], v[164:167], v[190:193], v[52:55]
	v_mfma_f32_16x16x32_bf16 v[48:51], v[172:175], v[190:193], v[48:51]
	v_mfma_f32_16x16x32_bf16 v[36:39], v[164:167], v[198:201], v[36:39]
	v_mfma_f32_16x16x32_bf16 v[32:35], v[172:175], v[198:201], v[32:35]
	v_mfma_f32_16x16x32_bf16 v[20:23], v[164:167], v[206:209], v[20:23]
	v_mfma_f32_16x16x32_bf16 v[16:19], v[172:175], v[206:209], v[16:19]
	v_mfma_f32_16x16x32_bf16 v[4:7], v[164:167], v[214:217], v[4:7]
	v_mfma_f32_16x16x32_bf16 v[0:3], v[172:175], v[214:217], v[0:3]
	s_setprio 0
	s_barrier
	s_add_i32 s78, 0, 0x18000
	s_add_i32 s79, 0, 0x1c000
	v_add_u32_e32 v140, s78, v181
	v_add_u32_e32 v172, s79, v181
	ds_read_b128 v[128:131], v140
	ds_read_b128 v[132:135], v140 offset:1024
	ds_read_b128 v[136:139], v140 offset:2048
	ds_read_b128 v[140:143], v140 offset:3072
	ds_read_b128 v[160:163], v172
	ds_read_b128 v[164:167], v172 offset:1024
	ds_read_b128 v[168:171], v172 offset:2048
	ds_read_b128 v[172:175], v172 offset:3072
	s_add_u32 s38, s38, 0xb0000
	s_addc_u32 s39, s39, 0
	s_mov_b32 m0, s53
	v_lshl_add_u64 v[226:227], s[38:39], 0, v[144:145]
	ds_read_b128 v[186:189], v184 offset:32768
	ds_read_b128 v[190:193], v184 offset:33792
	ds_read_b128 v[194:197], v184 offset:34816
	ds_read_b128 v[198:201], v184 offset:35840
	ds_read_b128 v[202:205], v184 offset:36864
	ds_read_b128 v[206:209], v184 offset:37888
	ds_read_b128 v[210:213], v184 offset:38912
	ds_read_b128 v[214:217], v184 offset:39936
	global_load_lds_dwordx4 v[226:227], off
	v_lshl_add_u64 v[226:227], s[38:39], 0, v[148:149]
	s_mov_b32 m0, s54
	s_nop 0
	global_load_lds_dwordx4 v[226:227], off
	s_waitcnt vmcnt(8)
	s_waitcnt lgkmcnt(0)
	s_barrier
	s_setprio 1
	s_waitcnt lgkmcnt(0)
	v_mfma_f32_16x16x32_bf16 v[124:127], v[128:131], v[186:189], v[124:127]
	v_mfma_f32_16x16x32_bf16 v[120:123], v[136:139], v[186:189], v[120:123]
	v_mfma_f32_16x16x32_bf16 v[108:111], v[128:131], v[194:197], v[108:111]
	v_mfma_f32_16x16x32_bf16 v[104:107], v[136:139], v[194:197], v[104:107]
	v_mfma_f32_16x16x32_bf16 v[92:95], v[128:131], v[202:205], v[92:95]
	v_mfma_f32_16x16x32_bf16 v[88:91], v[136:139], v[202:205], v[88:91]
	v_mfma_f32_16x16x32_bf16 v[76:79], v[128:131], v[210:213], v[76:79]
	v_mfma_f32_16x16x32_bf16 v[72:75], v[136:139], v[210:213], v[72:75]
	v_mfma_f32_16x16x32_bf16 v[124:127], v[132:135], v[190:193], v[124:127]
	v_mfma_f32_16x16x32_bf16 v[120:123], v[140:143], v[190:193], v[120:123]
	v_mfma_f32_16x16x32_bf16 v[108:111], v[132:135], v[198:201], v[108:111]
	v_mfma_f32_16x16x32_bf16 v[104:107], v[140:143], v[198:201], v[104:107]
	v_mfma_f32_16x16x32_bf16 v[92:95], v[132:135], v[206:209], v[92:95]
	v_mfma_f32_16x16x32_bf16 v[88:91], v[140:143], v[206:209], v[88:91]
	v_mfma_f32_16x16x32_bf16 v[76:79], v[132:135], v[214:217], v[76:79]
	v_mfma_f32_16x16x32_bf16 v[72:75], v[140:143], v[214:217], v[72:75]
	s_setprio 0
	s_setprio 1
	v_mfma_f32_16x16x32_bf16 v[116:119], v[160:163], v[186:189], v[116:119]
	v_mfma_f32_16x16x32_bf16 v[112:115], v[168:171], v[186:189], v[112:115]
	v_mfma_f32_16x16x32_bf16 v[100:103], v[160:163], v[194:197], v[100:103]
	v_mfma_f32_16x16x32_bf16 v[96:99], v[168:171], v[194:197], v[96:99]
	v_mfma_f32_16x16x32_bf16 v[84:87], v[160:163], v[202:205], v[84:87]
	v_mfma_f32_16x16x32_bf16 v[80:83], v[168:171], v[202:205], v[80:83]
	v_mfma_f32_16x16x32_bf16 v[68:71], v[160:163], v[210:213], v[68:71]
	v_mfma_f32_16x16x32_bf16 v[64:67], v[168:171], v[210:213], v[64:67]
	v_mfma_f32_16x16x32_bf16 v[116:119], v[164:167], v[190:193], v[116:119]
	v_mfma_f32_16x16x32_bf16 v[112:115], v[172:175], v[190:193], v[112:115]
	v_mfma_f32_16x16x32_bf16 v[100:103], v[164:167], v[198:201], v[100:103]
	v_mfma_f32_16x16x32_bf16 v[96:99], v[172:175], v[198:201], v[96:99]
	v_mfma_f32_16x16x32_bf16 v[84:87], v[164:167], v[206:209], v[84:87]
	v_mfma_f32_16x16x32_bf16 v[80:83], v[172:175], v[206:209], v[80:83]
	v_mfma_f32_16x16x32_bf16 v[68:71], v[164:167], v[214:217], v[68:71]
	v_mfma_f32_16x16x32_bf16 v[64:67], v[172:175], v[214:217], v[64:67]
	s_setprio 0
	s_barrier
; #define PG8_STAGE(bufoff, gbase, voff) do { _Pragma("unroll") for (int _i = 0; _i < 2; ++_i) \
;         __builtin_amdgcn_global_load_lds((const unsigned*)((const char*)(gbase) + (voff)[_i]), (LAS unsigned*)(lds + (bufoff) + ldsw + _i * 8192), 16, 0, 0); } while (0)
; #define PG8_LDA(dst, b, h) do { _Pragma("unroll") for (int m = 0; m < 4; ++m) _Pragma("unroll") for (int k = 0; k < 2; ++k) dst[m][k] = *(const LAS bf16x8*)(lds + PG8_SA(b, h) + aoff + m * 2048 + k * 1024); } while (0)
; #define PG8_MMA(ai, bj, At, Bt) do { __builtin_amdgcn_s_setprio(1); _Pragma("unroll") for (int m = 0; m < 4; ++m) _Pragma("unroll") for (int n = 0; n < 2; ++n) _Pragma("unroll") for (int k = 0; k < 2; ++k) \
;         acc[ai][bj][m][n] = __builtin_amdgcn_mfma_f32_16x16x32_bf16(Bt[n][k], At[m][k], acc[ai][bj][m][n], 0, 0, 0); __builtin_amdgcn_s_setprio(0); } while (0)
; #define PG8_WAIT_V(n) asm volatile("s_waitcnt vmcnt(" #n ")" ::: "memory")
; #define PG8_WAIT_L(n) asm volatile("s_waitcnt lgkmcnt(" #n ")" ::: "memory")
; #define PG8_BAR __builtin_amdgcn_s_barrier()
; #define PG8_SCHED __builtin_amdgcn_sched_barrier(0)
; template <class Epi>
; __device__ __forceinline__ void gemm_phase(LAS unsigned char* lds, const Gemm g, const StaticOrder& S, const Epi& E) {
;     ...
;             PG8_LDA(At, 1, 1); PG8_STAGE(PG8_SB(1, 0), b3, voffB); PG8_STAGE(PG8_SB(1, 1), b3 + hstepB, voffB); PG8_STAGE(PG8_SA(1, 0), a3, voffA);
;             PG8_WAIT_V(8); PG8_WAIT_L(0); PG8_BAR; PG8_MMA(1, 0, At, B0); PG8_MMA(1, 1, At, B1); PG8_BAR; PG8_SCHED;
;         }
	s_add_i32 s38, s78, s42
	v_lshl_add_u64 v[178:179], v[178:179], 0, s[16:17]
	s_mov_b32 m0, s38
	ds_read_b128 v[186:189], v184 offset:49152
	ds_read_b128 v[190:193], v184 offset:50176
	ds_read_b128 v[194:197], v184 offset:51200
	ds_read_b128 v[198:201], v184 offset:52224
	ds_read_b128 v[202:205], v184 offset:53248
	ds_read_b128 v[206:209], v184 offset:54272
	ds_read_b128 v[210:213], v184 offset:55296
	ds_read_b128 v[214:217], v184 offset:56320
	global_load_lds_dwordx4 v[178:179], off
	s_add_i32 m0, s38, 0x2000
	s_add_u32 s34, s34, 0xb0080
	v_lshl_add_u64 v[178:179], v[218:219], 0, s[16:17]
	s_addc_u32 s35, s35, 0
	s_add_i32 s38, s79, s42
	global_load_lds_dwordx4 v[178:179], off
	v_lshl_add_u64 v[178:179], s[34:35], 0, v[146:147]
	s_mov_b32 m0, s38
	s_nop 0
	global_load_lds_dwordx4 v[178:179], off
	v_lshl_add_u64 v[178:179], s[34:35], 0, v[150:151]
	s_add_i32 m0, s38, 0x2000
	s_nop 0
	global_load_lds_dwordx4 v[178:179], off
	v_lshl_add_u64 v[178:179], v[220:221], 0, s[16:17]
	s_mov_b32 m0, s62
	s_nop 0
	global_load_lds_dwordx4 v[178:179], off
	v_lshl_add_u64 v[178:179], v[222:223], 0, s[16:17]
	s_mov_b32 m0, s63
	s_nop 0
	global_load_lds_dwordx4 v[178:179], off
	s_waitcnt vmcnt(8)
	s_waitcnt lgkmcnt(0)
	s_barrier
	s_setprio 1
	s_waitcnt lgkmcnt(0)
	v_mfma_f32_16x16x32_bf16 v[60:63], v[128:131], v[186:189], v[60:63]
	v_mfma_f32_16x16x32_bf16 v[56:59], v[136:139], v[186:189], v[56:59]
	v_mfma_f32_16x16x32_bf16 v[44:47], v[128:131], v[194:197], v[44:47]
	v_mfma_f32_16x16x32_bf16 v[40:43], v[136:139], v[194:197], v[40:43]
	v_mfma_f32_16x16x32_bf16 v[28:31], v[128:131], v[202:205], v[28:31]
	v_mfma_f32_16x16x32_bf16 v[24:27], v[136:139], v[202:205], v[24:27]
	v_mfma_f32_16x16x32_bf16 v[12:15], v[128:131], v[210:213], v[12:15]
	v_mfma_f32_16x16x32_bf16 v[8:11], v[136:139], v[210:213], v[8:11]
	v_mfma_f32_16x16x32_bf16 v[60:63], v[132:135], v[190:193], v[60:63]
	v_mfma_f32_16x16x32_bf16 v[56:59], v[140:143], v[190:193], v[56:59]
	v_mfma_f32_16x16x32_bf16 v[44:47], v[132:135], v[198:201], v[44:47]
	v_mfma_f32_16x16x32_bf16 v[40:43], v[140:143], v[198:201], v[40:43]
	v_mfma_f32_16x16x32_bf16 v[28:31], v[132:135], v[206:209], v[28:31]
	v_mfma_f32_16x16x32_bf16 v[24:27], v[140:143], v[206:209], v[24:27]
	v_mfma_f32_16x16x32_bf16 v[12:15], v[132:135], v[214:217], v[12:15]
	v_mfma_f32_16x16x32_bf16 v[8:11], v[140:143], v[214:217], v[8:11]
	s_setprio 0
	s_setprio 1
	v_mfma_f32_16x16x32_bf16 v[52:55], v[160:163], v[186:189], v[52:55]
	v_mfma_f32_16x16x32_bf16 v[48:51], v[168:171], v[186:189], v[48:51]
	v_mfma_f32_16x16x32_bf16 v[36:39], v[160:163], v[194:197], v[36:39]
	v_mfma_f32_16x16x32_bf16 v[32:35], v[168:171], v[194:197], v[32:35]
	v_mfma_f32_16x16x32_bf16 v[20:23], v[160:163], v[202:205], v[20:23]
	v_mfma_f32_16x16x32_bf16 v[16:19], v[168:171], v[202:205], v[16:19]
	v_mfma_f32_16x16x32_bf16 v[4:7], v[160:163], v[210:213], v[4:7]
	v_mfma_f32_16x16x32_bf16 v[0:3], v[168:171], v[210:213], v[0:3]
	v_mfma_f32_16x16x32_bf16 v[52:55], v[164:167], v[190:193], v[52:55]
	v_mfma_f32_16x16x32_bf16 v[48:51], v[172:175], v[190:193], v[48:51]
	v_mfma_f32_16x16x32_bf16 v[36:39], v[164:167], v[198:201], v[36:39]
	v_mfma_f32_16x16x32_bf16 v[32:35], v[172:175], v[198:201], v[32:35]
	v_mfma_f32_16x16x32_bf16 v[20:23], v[164:167], v[206:209], v[20:23]
	v_mfma_f32_16x16x32_bf16 v[16:19], v[172:175], v[206:209], v[16:19]
	v_mfma_f32_16x16x32_bf16 v[4:7], v[164:167], v[214:217], v[4:7]
	v_mfma_f32_16x16x32_bf16 v[0:3], v[172:175], v[214:217], v[0:3]
	s_setprio 0
	s_barrier
	s_add_i32 s77, s77, 2
	s_add_u32 s0, s0, 0x100
	s_addc_u32 s1, s1, 0
	s_add_u32 s75, s75, 0x100
	s_addc_u32 s76, s76, 0
	s_cmp_gt_u32 s77, 41

; #define PG8_STAGE(bufoff, gbase, voff) do { _Pragma("unroll") for (int _i = 0; _i < 2; ++_i) \
;         __builtin_amdgcn_global_load_lds((const unsigned*)((const char*)(gbase) + (voff)[_i]), (LAS unsigned*)(lds + (bufoff) + ldsw + _i * 8192), 16, 0, 0); } while (0)
; #define PG8_LDA(dst, b, h) do { _Pragma("unroll") for (int m = 0; m < 4; ++m) _Pragma("unroll") for (int k = 0; k < 2; ++k) dst[m][k] = *(const LAS bf16x8*)(lds + PG8_SA(b, h) + aoff + m * 2048 + k * 1024); } while (0)
; #define PG8_LDB(dst, b, h) do { _Pragma("unroll") for (int n = 0; n < 2; ++n) _Pragma("unroll") for (int k = 0; k < 2; ++k) dst[n][k] = *(const LAS bf16x8*)(lds + PG8_SB(b, h) + boff + n * 2048 + k * 1024); } while (0)
; #define PG8_MMA(ai, bj, At, Bt) do { __builtin_amdgcn_s_setprio(1); _Pragma("unroll") for (int m = 0; m < 4; ++m) _Pragma("unroll") for (int n = 0; n < 2; ++n) _Pragma("unroll") for (int k = 0; k < 2; ++k) \
;         acc[ai][bj][m][n] = __builtin_amdgcn_mfma_f32_16x16x32_bf16(Bt[n][k], At[m][k], acc[ai][bj][m][n], 0, 0, 0); __builtin_amdgcn_s_setprio(0); } while (0)
; #define PG8_BAR __builtin_amdgcn_s_barrier()
; template <class Epi>
; __device__ __forceinline__ void gemm_phase(LAS unsigned char* lds, const Gemm g, const StaticOrder& S, const Epi& E) {
;     ...
;         const bool has_next = S.next(ui + 1, nxt);
;         const char* nA = has_next ? (const char*)g.A + (size_t)nxt.pm * tstepA : cA; const char* nB = has_next ? (const char*)g.Bt + (size_t)nxt.pn * tstepB : cB;
; #pragma nounroll
;         for (int t = 0; t < nt; t += 2) {
;             const bool last = (t == nt - 2);
;             const char* a1 = cA + (size_t)(t + 1) * kstep;
;             const char* a2 = last ? nA : cA + (size_t)(t + 2) * kstep; const char* b2 = last ? nB : cB + (size_t)(t + 2) * kstep;
;             const char* a3 = a2 + kstep; const char* b3 = b2 + kstep;
;             PG8_LDB(B0, 0, 0); PG8_LDB(B1, 0, 1); PG8_SCHED; PG8_LDA(At, 0, 0); PG8_STAGE(PG8_SA(1, 1), a1 + hstepA, voffA);
;             PG8_WAIT_V(8); PG8_WAIT_L(0); PG8_BAR; PG8_MMA(0, 0, At, B0); PG8_MMA(0, 1, At, B1); PG8_BAR; PG8_SCHED;
;             PG8_LDA(At, 0, 1); PG8_STAGE(PG8_SB(0, 0), b2, voffB); PG8_STAGE(PG8_SB(0, 1), b2 + hstepB, voffB); PG8_STAGE(PG8_SA(0, 0), a2, voffA);
;             PG8_WAIT_V(8); PG8_WAIT_L(0); PG8_BAR; PG8_MMA(1, 0, At, B0); PG8_MMA(1, 1, At, B1); PG8_BAR; PG8_SCHED;
.LBB0_888:
	s_ashr_i32 s43, s42, 31
	s_lshl_b64 s[52:53], s[42:43], 19
	s_add_u32 s52, s30, s52
	s_addc_u32 s53, s31, s53
	s_and_b64 s[54:55], s[4:5], exec
	s_cselect_b32 s7, s53, s57
	s_cselect_b32 s9, s52, s56
	s_ashr_i32 s39, s38, 31
	s_lshl_b64 s[54:55], s[38:39], 19
	s_add_u32 s54, s3, s54
	s_addc_u32 s55, s33, s55
	s_and_b64 s[64:65], s[4:5], exec
	s_cselect_b32 s39, s55, s63
	s_cselect_b32 s43, s54, s62
	s_add_u32 s56, s56, 0x40080
	s_addc_u32 s57, s57, 0
	s_add_u32 s83, s62, 0x100
	s_addc_u32 s84, s63, 0
	s_mov_b32 s85, -2
	s_waitcnt lgkmcnt(0)
	s_nop 0
	ds_read_b128 v[40:43], v208
	ds_read_b128 v[44:47], v208 offset:1024
	ds_read_b128 v[56:59], v208 offset:2048
	ds_read_b128 v[60:63], v208 offset:3072
	ds_read_b128 v[144:147], v209
	ds_read_b128 v[148:151], v209 offset:1024
	ds_read_b128 v[152:155], v209 offset:2048
	ds_read_b128 v[156:159], v209 offset:3072
	s_add_u32 s62, s56, 0xfffc0080
	s_addc_u32 s63, s57, -1
	s_cmp_eq_u32 s85, 12
	s_cselect_b32 s65, s7, s63
	s_cselect_b32 s64, s9, s62
	s_cselect_b32 s63, s39, s84
	s_cselect_b32 s62, s43, s83
	v_lshl_add_u64 v[218:219], s[56:57], 0, v[178:179]
	s_add_i32 m0, s69, 0xc000
	ds_read_b128 v[160:163], v210
	ds_read_b128 v[164:167], v210 offset:1024
	ds_read_b128 v[186:189], v210 offset:2048
	ds_read_b128 v[190:193], v210 offset:3072
	ds_read_b128 v[194:197], v210 offset:4096
	ds_read_b128 v[198:201], v210 offset:5120
	ds_read_b128 v[202:205], v210 offset:6144
	ds_read_b128 v[214:217], v210 offset:7168
	global_load_lds_dwordx4 v[218:219], off
	v_lshl_add_u64 v[218:219], s[56:57], 0, v[180:181]
	s_add_i32 m0, s69, 0xe000
	s_nop 0
	global_load_lds_dwordx4 v[218:219], off
	s_waitcnt vmcnt(8)
	s_waitcnt lgkmcnt(0)
	s_barrier
	s_setprio 1
	s_waitcnt lgkmcnt(0)
	v_mfma_f32_16x16x32_bf16 v[140:143], v[40:43], v[160:163], 0
	v_mfma_f32_16x16x32_bf16 v[136:139], v[56:59], v[160:163], 0
	v_mfma_f32_16x16x32_bf16 v[124:127], v[40:43], v[186:189], 0
	v_mfma_f32_16x16x32_bf16 v[120:123], v[56:59], v[186:189], 0
	v_mfma_f32_16x16x32_bf16 v[108:111], v[40:43], v[194:197], 0
	v_mfma_f32_16x16x32_bf16 v[104:107], v[56:59], v[194:197], 0
	v_mfma_f32_16x16x32_bf16 v[92:95], v[40:43], v[202:205], 0
	v_mfma_f32_16x16x32_bf16 v[88:91], v[56:59], v[202:205], 0
	v_mfma_f32_16x16x32_bf16 v[140:143], v[44:47], v[164:167], v[140:143]
	v_mfma_f32_16x16x32_bf16 v[136:139], v[60:63], v[164:167], v[136:139]
	v_mfma_f32_16x16x32_bf16 v[124:127], v[44:47], v[190:193], v[124:127]
	v_mfma_f32_16x16x32_bf16 v[120:123], v[60:63], v[190:193], v[120:123]
	v_mfma_f32_16x16x32_bf16 v[108:111], v[44:47], v[198:201], v[108:111]
	v_mfma_f32_16x16x32_bf16 v[104:107], v[60:63], v[198:201], v[104:107]
	v_mfma_f32_16x16x32_bf16 v[92:95], v[44:47], v[214:217], v[92:95]
	v_mfma_f32_16x16x32_bf16 v[88:91], v[60:63], v[214:217], v[88:91]
	s_setprio 0
	s_setprio 1
	v_mfma_f32_16x16x32_bf16 v[132:135], v[144:147], v[160:163], 0
	v_mfma_f32_16x16x32_bf16 v[128:131], v[152:155], v[160:163], 0
	v_mfma_f32_16x16x32_bf16 v[116:119], v[144:147], v[186:189], 0
	v_mfma_f32_16x16x32_bf16 v[112:115], v[152:155], v[186:189], 0
	v_mfma_f32_16x16x32_bf16 v[100:103], v[144:147], v[194:197], 0
	v_mfma_f32_16x16x32_bf16 v[96:99], v[152:155], v[194:197], 0
	v_mfma_f32_16x16x32_bf16 v[84:87], v[144:147], v[202:205], 0
	v_mfma_f32_16x16x32_bf16 v[80:83], v[152:155], v[202:205], 0
	v_mfma_f32_16x16x32_bf16 v[132:135], v[148:151], v[164:167], v[132:135]
	v_mfma_f32_16x16x32_bf16 v[128:131], v[156:159], v[164:167], v[128:131]
	v_mfma_f32_16x16x32_bf16 v[116:119], v[148:151], v[190:193], v[116:119]
	v_mfma_f32_16x16x32_bf16 v[112:115], v[156:159], v[190:193], v[112:115]
	v_mfma_f32_16x16x32_bf16 v[100:103], v[148:151], v[198:201], v[100:103]
	v_mfma_f32_16x16x32_bf16 v[96:99], v[156:159], v[198:201], v[96:99]
	v_mfma_f32_16x16x32_bf16 v[84:87], v[148:151], v[214:217], v[84:87]
	v_mfma_f32_16x16x32_bf16 v[80:83], v[156:159], v[214:217], v[80:83]
	s_setprio 0
	s_barrier
	s_add_i32 s86, s81, s68
	v_lshl_add_u64 v[218:219], s[62:63], 0, v[170:171]
	s_mov_b32 m0, s86
	ds_read_b128 v[160:163], v210 offset:16384
	ds_read_b128 v[164:167], v210 offset:17408
	ds_read_b128 v[186:189], v210 offset:18432
	ds_read_b128 v[190:193], v210 offset:19456
	ds_read_b128 v[194:197], v210 offset:20480
	ds_read_b128 v[198:201], v210 offset:21504
	ds_read_b128 v[202:205], v210 offset:22528
	ds_read_b128 v[214:217], v210 offset:23552
	global_load_lds_dwordx4 v[218:219], off
	s_add_i32 m0, s86, 0x2000
	s_add_u32 s86, s62, 0x40000
	v_lshl_add_u64 v[220:221], s[62:63], 0, v[174:175]
	s_addc_u32 s87, s63, 0
	s_add_i32 s88, s82, s68
	global_load_lds_dwordx4 v[220:221], off
	v_lshl_add_u64 v[222:223], s[86:87], 0, v[170:171]
	s_mov_b32 m0, s88
	v_lshl_add_u64 v[226:227], s[64:65], 0, v[172:173]
	global_load_lds_dwordx4 v[222:223], off
	v_lshl_add_u64 v[222:223], s[86:87], 0, v[174:175]
	s_add_i32 m0, s88, 0x2000
	s_nop 0
	global_load_lds_dwordx4 v[222:223], off
	v_lshl_add_u64 v[222:223], s[64:65], 0, v[168:169]
	s_mov_b32 m0, s69
	s_nop 0
	global_load_lds_dwordx4 v[222:223], off
	s_mov_b32 m0, s70
	s_nop 0
	global_load_lds_dwordx4 v[226:227], off
	s_waitcnt vmcnt(8)
	s_waitcnt lgkmcnt(0)
	s_barrier
; #define PG8_STAGE(bufoff, gbase, voff) do { _Pragma("unroll") for (int _i = 0; _i < 2; ++_i) \
;         __builtin_amdgcn_global_load_lds((const unsigned*)((const char*)(gbase) + (voff)[_i]), (LAS unsigned*)(lds + (bufoff) + ldsw + _i * 8192), 16, 0, 0); } while (0)
; #define PG8_LDA(dst, b, h) do { _Pragma("unroll") for (int m = 0; m < 4; ++m) _Pragma("unroll") for (int k = 0; k < 2; ++k) dst[m][k] = *(const LAS bf16x8*)(lds + PG8_SA(b, h) + aoff + m * 2048 + k * 1024); } while (0)
; #define PG8_LDB(dst, b, h) do { _Pragma("unroll") for (int n = 0; n < 2; ++n) _Pragma("unroll") for (int k = 0; k < 2; ++k) dst[n][k] = *(const LAS bf16x8*)(lds + PG8_SB(b, h) + boff + n * 2048 + k * 1024); } while (0)
; #define PG8_MMA(ai, bj, At, Bt) do { __builtin_amdgcn_s_setprio(1); _Pragma("unroll") for (int m = 0; m < 4; ++m) _Pragma("unroll") for (int n = 0; n < 2; ++n) _Pragma("unroll") for (int k = 0; k < 2; ++k) \
;         acc[ai][bj][m][n] = __builtin_amdgcn_mfma_f32_16x16x32_bf16(Bt[n][k], At[m][k], acc[ai][bj][m][n], 0, 0, 0); __builtin_amdgcn_s_setprio(0); } while (0)
; #define PG8_WAIT_V(n) asm volatile("s_waitcnt vmcnt(" #n ")" ::: "memory")
; #define PG8_WAIT_L(n) asm volatile("s_waitcnt lgkmcnt(" #n ")" ::: "memory")
; #define PG8_BAR __builtin_amdgcn_s_barrier()
; #define PG8_SCHED __builtin_amdgcn_sched_barrier(0)
; template <class Epi>
; __device__ __forceinline__ void gemm_phase(LAS unsigned char* lds, const Gemm g, const StaticOrder& S, const Epi& E) {
;     ...
;             PG8_WAIT_V(8); PG8_WAIT_L(0); PG8_BAR; PG8_MMA(1, 0, At, B0); PG8_MMA(1, 1, At, B1); PG8_BAR; PG8_SCHED;
;             PG8_LDB(B0, 1, 0); PG8_LDB(B1, 1, 1); PG8_SCHED; PG8_LDA(At, 1, 0); PG8_STAGE(PG8_SA(0, 1), a2 + hstepA, voffA);
;             PG8_WAIT_V(8); PG8_WAIT_L(0); PG8_BAR; PG8_MMA(0, 0, At, B0); PG8_MMA(0, 1, At, B1); PG8_BAR; PG8_SCHED;
;             PG8_LDA(At, 1, 1); PG8_STAGE(PG8_SB(1, 0), b3, voffB); PG8_STAGE(PG8_SB(1, 1), b3 + hstepB, voffB); PG8_STAGE(PG8_SA(1, 0), a3, voffA);
;             PG8_WAIT_V(8); PG8_WAIT_L(0); PG8_BAR; PG8_MMA(1, 0, At, B0); PG8_MMA(1, 1, At, B1); PG8_BAR; PG8_SCHED;
	s_setprio 1
	s_waitcnt lgkmcnt(0)
	v_mfma_f32_16x16x32_bf16 v[76:79], v[40:43], v[160:163], 0
	v_mfma_f32_16x16x32_bf16 v[72:75], v[56:59], v[160:163], 0
	v_mfma_f32_16x16x32_bf16 v[52:55], v[40:43], v[186:189], 0
	v_mfma_f32_16x16x32_bf16 v[48:51], v[56:59], v[186:189], 0
	v_mfma_f32_16x16x32_bf16 v[28:31], v[40:43], v[194:197], 0
	v_mfma_f32_16x16x32_bf16 v[24:27], v[56:59], v[194:197], 0
	v_mfma_f32_16x16x32_bf16 v[12:15], v[40:43], v[202:205], 0
	v_mfma_f32_16x16x32_bf16 v[8:11], v[56:59], v[202:205], 0
	v_mfma_f32_16x16x32_bf16 v[76:79], v[44:47], v[164:167], v[76:79]
	v_mfma_f32_16x16x32_bf16 v[72:75], v[60:63], v[164:167], v[72:75]
	v_mfma_f32_16x16x32_bf16 v[52:55], v[44:47], v[190:193], v[52:55]
	v_mfma_f32_16x16x32_bf16 v[48:51], v[60:63], v[190:193], v[48:51]
	v_mfma_f32_16x16x32_bf16 v[28:31], v[44:47], v[198:201], v[28:31]
	v_mfma_f32_16x16x32_bf16 v[24:27], v[60:63], v[198:201], v[24:27]
	v_mfma_f32_16x16x32_bf16 v[12:15], v[44:47], v[214:217], v[12:15]
	v_mfma_f32_16x16x32_bf16 v[8:11], v[60:63], v[214:217], v[8:11]
	s_setprio 0
	s_setprio 1
	v_mfma_f32_16x16x32_bf16 v[36:39], v[144:147], v[186:189], 0
	v_mfma_f32_16x16x32_bf16 v[32:35], v[152:155], v[186:189], 0
	v_mfma_f32_16x16x32_bf16 v[20:23], v[144:147], v[194:197], 0
	v_mfma_f32_16x16x32_bf16 v[16:19], v[152:155], v[194:197], 0
	v_mfma_f32_16x16x32_bf16 v[4:7], v[144:147], v[202:205], 0
	v_mfma_f32_16x16x32_bf16 v[0:3], v[152:155], v[202:205], 0
	v_mfma_f32_16x16x32_bf16 v[40:43], v[144:147], v[160:163], 0
	v_mfma_f32_16x16x32_bf16 v[44:47], v[152:155], v[160:163], 0
	v_mfma_f32_16x16x32_bf16 v[36:39], v[148:151], v[190:193], v[36:39]
	v_mfma_f32_16x16x32_bf16 v[32:35], v[156:159], v[190:193], v[32:35]
	v_mfma_f32_16x16x32_bf16 v[20:23], v[148:151], v[198:201], v[20:23]
	v_mfma_f32_16x16x32_bf16 v[16:19], v[156:159], v[198:201], v[16:19]
	v_mfma_f32_16x16x32_bf16 v[4:7], v[148:151], v[214:217], v[4:7]
	v_mfma_f32_16x16x32_bf16 v[0:3], v[156:159], v[214:217], v[0:3]
	v_mfma_f32_16x16x32_bf16 v[40:43], v[148:151], v[164:167], v[40:43]
	v_mfma_f32_16x16x32_bf16 v[44:47], v[156:159], v[164:167], v[44:47]
	s_setprio 0
	s_barrier
	s_add_i32 s86, 0, 0x18000
	s_add_i32 s87, 0, 0x1c000
	v_add_u32_e32 v68, s86, v207
	v_add_u32_e32 v156, s87, v207
	ds_read_b128 v[56:59], v68
	ds_read_b128 v[60:63], v68 offset:1024
	ds_read_b128 v[64:67], v68 offset:2048
	ds_read_b128 v[68:71], v68 offset:3072
	ds_read_b128 v[144:147], v156
	ds_read_b128 v[148:151], v156 offset:1024
	ds_read_b128 v[152:155], v156 offset:2048
	ds_read_b128 v[156:159], v156 offset:3072
	s_add_u32 s64, s64, 0x40000
	s_addc_u32 s65, s65, 0
	s_mov_b32 m0, s71
	v_lshl_add_u64 v[228:229], s[64:65], 0, v[168:169]
	ds_read_b128 v[160:163], v210 offset:32768
	ds_read_b128 v[164:167], v210 offset:33792
	ds_read_b128 v[186:189], v210 offset:34816
	ds_read_b128 v[190:193], v210 offset:35840
	ds_read_b128 v[194:197], v210 offset:36864
	ds_read_b128 v[198:201], v210 offset:37888
	ds_read_b128 v[202:205], v210 offset:38912
	ds_read_b128 v[214:217], v210 offset:39936
	global_load_lds_dwordx4 v[228:229], off
	v_lshl_add_u64 v[228:229], s[64:65], 0, v[172:173]
	s_mov_b32 m0, s72
	s_nop 0
	global_load_lds_dwordx4 v[228:229], off
	s_waitcnt vmcnt(8)
	s_waitcnt lgkmcnt(0)
	s_barrier
	s_setprio 1
	s_waitcnt lgkmcnt(0)
	v_mfma_f32_16x16x32_bf16 v[140:143], v[56:59], v[160:163], v[140:143]
	v_mfma_f32_16x16x32_bf16 v[136:139], v[64:67], v[160:163], v[136:139]
	v_mfma_f32_16x16x32_bf16 v[124:127], v[56:59], v[186:189], v[124:127]
	v_mfma_f32_16x16x32_bf16 v[120:123], v[64:67], v[186:189], v[120:123]
	v_mfma_f32_16x16x32_bf16 v[108:111], v[56:59], v[194:197], v[108:111]
	v_mfma_f32_16x16x32_bf16 v[104:107], v[64:67], v[194:197], v[104:107]
	v_mfma_f32_16x16x32_bf16 v[92:95], v[56:59], v[202:205], v[92:95]
	v_mfma_f32_16x16x32_bf16 v[88:91], v[64:67], v[202:205], v[88:91]
	v_mfma_f32_16x16x32_bf16 v[140:143], v[60:63], v[164:167], v[140:143]
	v_mfma_f32_16x16x32_bf16 v[136:139], v[68:71], v[164:167], v[136:139]
	v_mfma_f32_16x16x32_bf16 v[124:127], v[60:63], v[190:193], v[124:127]
	v_mfma_f32_16x16x32_bf16 v[120:123], v[68:71], v[190:193], v[120:123]
	v_mfma_f32_16x16x32_bf16 v[108:111], v[60:63], v[198:201], v[108:111]
	v_mfma_f32_16x16x32_bf16 v[104:107], v[68:71], v[198:201], v[104:107]
	v_mfma_f32_16x16x32_bf16 v[92:95], v[60:63], v[214:217], v[92:95]
	v_mfma_f32_16x16x32_bf16 v[88:91], v[68:71], v[214:217], v[88:91]
	s_setprio 0
	s_setprio 1
	v_mfma_f32_16x16x32_bf16 v[132:135], v[144:147], v[160:163], v[132:135]
	v_mfma_f32_16x16x32_bf16 v[128:131], v[152:155], v[160:163], v[128:131]
	v_mfma_f32_16x16x32_bf16 v[116:119], v[144:147], v[186:189], v[116:119]
	v_mfma_f32_16x16x32_bf16 v[112:115], v[152:155], v[186:189], v[112:115]
	v_mfma_f32_16x16x32_bf16 v[100:103], v[144:147], v[194:197], v[100:103]
	v_mfma_f32_16x16x32_bf16 v[96:99], v[152:155], v[194:197], v[96:99]
	v_mfma_f32_16x16x32_bf16 v[84:87], v[144:147], v[202:205], v[84:87]
	v_mfma_f32_16x16x32_bf16 v[80:83], v[152:155], v[202:205], v[80:83]
	v_mfma_f32_16x16x32_bf16 v[132:135], v[148:151], v[164:167], v[132:135]
	v_mfma_f32_16x16x32_bf16 v[128:131], v[156:159], v[164:167], v[128:131]
	v_mfma_f32_16x16x32_bf16 v[116:119], v[148:151], v[190:193], v[116:119]
	v_mfma_f32_16x16x32_bf16 v[112:115], v[156:159], v[190:193], v[112:115]
	v_mfma_f32_16x16x32_bf16 v[100:103], v[148:151], v[198:201], v[100:103]
	v_mfma_f32_16x16x32_bf16 v[96:99], v[156:159], v[198:201], v[96:99]
	v_mfma_f32_16x16x32_bf16 v[84:87], v[148:151], v[214:217], v[84:87]
	v_mfma_f32_16x16x32_bf16 v[80:83], v[156:159], v[214:217], v[80:83]
	s_setprio 0
	s_barrier
; #define PG8_STAGE(bufoff, gbase, voff) do { _Pragma("unroll") for (int _i = 0; _i < 2; ++_i) \
;         __builtin_amdgcn_global_load_lds((const unsigned*)((const char*)(gbase) + (voff)[_i]), (LAS unsigned*)(lds + (bufoff) + ldsw + _i * 8192), 16, 0, 0); } while (0)
; #define PG8_LDA(dst, b, h) do { _Pragma("unroll") for (int m = 0; m < 4; ++m) _Pragma("unroll") for (int k = 0; k < 2; ++k) dst[m][k] = *(const LAS bf16x8*)(lds + PG8_SA(b, h) + aoff + m * 2048 + k * 1024); } while (0)
; #define PG8_MMA(ai, bj, At, Bt) do { __builtin_amdgcn_s_setprio(1); _Pragma("unroll") for (int m = 0; m < 4; ++m) _Pragma("unroll") for (int n = 0; n < 2; ++n) _Pragma("unroll") for (int k = 0; k < 2; ++k) \
;         acc[ai][bj][m][n] = __builtin_amdgcn_mfma_f32_16x16x32_bf16(Bt[n][k], At[m][k], acc[ai][bj][m][n], 0, 0, 0); __builtin_amdgcn_s_setprio(0); } while (0)
; #define PG8_WAIT_V(n) asm volatile("s_waitcnt vmcnt(" #n ")" ::: "memory")
; #define PG8_WAIT_L(n) asm volatile("s_waitcnt lgkmcnt(" #n ")" ::: "memory")
; #define PG8_BAR __builtin_amdgcn_s_barrier()
; #define PG8_SCHED __builtin_amdgcn_sched_barrier(0)
; template <class Epi>
; __device__ __forceinline__ void gemm_phase(LAS unsigned char* lds, const Gemm g, const StaticOrder& S, const Epi& E) {
;     ...
;             PG8_LDA(At, 1, 1); PG8_STAGE(PG8_SB(1, 0), b3, voffB); PG8_STAGE(PG8_SB(1, 1), b3 + hstepB, voffB); PG8_STAGE(PG8_SA(1, 0), a3, voffA);
;             PG8_WAIT_V(8); PG8_WAIT_L(0); PG8_BAR; PG8_MMA(1, 0, At, B0); PG8_MMA(1, 1, At, B1); PG8_BAR; PG8_SCHED;
;         }
	s_add_i32 s64, s86, s68
	v_lshl_add_u64 v[218:219], v[218:219], 0, s[18:19]
	s_mov_b32 m0, s64
	ds_read_b128 v[160:163], v210 offset:49152
	ds_read_b128 v[164:167], v210 offset:50176
	ds_read_b128 v[186:189], v210 offset:51200
	ds_read_b128 v[190:193], v210 offset:52224
	ds_read_b128 v[194:197], v210 offset:53248
	ds_read_b128 v[198:201], v210 offset:54272
	ds_read_b128 v[202:205], v210 offset:55296
	ds_read_b128 v[214:217], v210 offset:56320
	global_load_lds_dwordx4 v[218:219], off
	s_add_i32 m0, s64, 0x2000
	s_add_u32 s62, s62, 0x40080
	v_lshl_add_u64 v[218:219], v[220:221], 0, s[18:19]
	s_addc_u32 s63, s63, 0
	s_add_i32 s64, s87, s68
	global_load_lds_dwordx4 v[218:219], off
	v_lshl_add_u64 v[218:219], s[62:63], 0, v[170:171]
	s_mov_b32 m0, s64
	s_nop 0
	global_load_lds_dwordx4 v[218:219], off
	v_lshl_add_u64 v[218:219], s[62:63], 0, v[174:175]
	s_add_i32 m0, s64, 0x2000
	s_nop 0
	global_load_lds_dwordx4 v[218:219], off
	v_lshl_add_u64 v[218:219], v[222:223], 0, s[18:19]
	s_mov_b32 m0, s76
	s_nop 0
	global_load_lds_dwordx4 v[218:219], off
	v_lshl_add_u64 v[218:219], v[226:227], 0, s[18:19]
	s_mov_b32 m0, s77
	s_nop 0
	global_load_lds_dwordx4 v[218:219], off
	s_waitcnt vmcnt(8)
	s_waitcnt lgkmcnt(0)
	s_barrier
	s_setprio 1
	s_waitcnt lgkmcnt(0)
	v_mfma_f32_16x16x32_bf16 v[76:79], v[56:59], v[160:163], v[76:79]
	v_mfma_f32_16x16x32_bf16 v[72:75], v[64:67], v[160:163], v[72:75]
	v_mfma_f32_16x16x32_bf16 v[52:55], v[56:59], v[186:189], v[52:55]
	v_mfma_f32_16x16x32_bf16 v[48:51], v[64:67], v[186:189], v[48:51]
	v_mfma_f32_16x16x32_bf16 v[28:31], v[56:59], v[194:197], v[28:31]
	v_mfma_f32_16x16x32_bf16 v[24:27], v[64:67], v[194:197], v[24:27]
	v_mfma_f32_16x16x32_bf16 v[12:15], v[56:59], v[202:205], v[12:15]
	v_mfma_f32_16x16x32_bf16 v[8:11], v[64:67], v[202:205], v[8:11]
	v_mfma_f32_16x16x32_bf16 v[76:79], v[60:63], v[164:167], v[76:79]
	v_mfma_f32_16x16x32_bf16 v[72:75], v[68:71], v[164:167], v[72:75]
	v_mfma_f32_16x16x32_bf16 v[52:55], v[60:63], v[190:193], v[52:55]
	v_mfma_f32_16x16x32_bf16 v[48:51], v[68:71], v[190:193], v[48:51]
	v_mfma_f32_16x16x32_bf16 v[28:31], v[60:63], v[198:201], v[28:31]
	v_mfma_f32_16x16x32_bf16 v[24:27], v[68:71], v[198:201], v[24:27]
	v_mfma_f32_16x16x32_bf16 v[12:15], v[60:63], v[214:217], v[12:15]
	v_mfma_f32_16x16x32_bf16 v[8:11], v[68:71], v[214:217], v[8:11]
	s_setprio 0
	s_setprio 1
	v_mfma_f32_16x16x32_bf16 v[40:43], v[144:147], v[160:163], v[40:43]
	v_mfma_f32_16x16x32_bf16 v[68:71], v[148:151], v[164:167], v[40:43]
	v_mfma_f32_16x16x32_bf16 v[40:43], v[152:155], v[160:163], v[44:47]
	v_mfma_f32_16x16x32_bf16 v[36:39], v[144:147], v[186:189], v[36:39]
	v_mfma_f32_16x16x32_bf16 v[32:35], v[152:155], v[186:189], v[32:35]
	v_mfma_f32_16x16x32_bf16 v[20:23], v[144:147], v[194:197], v[20:23]
	v_mfma_f32_16x16x32_bf16 v[16:19], v[152:155], v[194:197], v[16:19]
	v_mfma_f32_16x16x32_bf16 v[4:7], v[144:147], v[202:205], v[4:7]
	v_mfma_f32_16x16x32_bf16 v[0:3], v[152:155], v[202:205], v[0:3]
	v_mfma_f32_16x16x32_bf16 v[64:67], v[156:159], v[164:167], v[40:43]
	v_mfma_f32_16x16x32_bf16 v[36:39], v[148:151], v[190:193], v[36:39]
	v_mfma_f32_16x16x32_bf16 v[32:35], v[156:159], v[190:193], v[32:35]
	v_mfma_f32_16x16x32_bf16 v[20:23], v[148:151], v[198:201], v[20:23]
	v_mfma_f32_16x16x32_bf16 v[16:19], v[156:159], v[198:201], v[16:19]
	v_mfma_f32_16x16x32_bf16 v[4:7], v[148:151], v[214:217], v[4:7]
	v_mfma_f32_16x16x32_bf16 v[0:3], v[156:159], v[214:217], v[0:3]
	s_setprio 0
	s_barrier
	s_add_i32 s85, s85, 2
	s_add_u32 s56, s56, 0x100
	s_addc_u32 s57, s57, 0
	s_add_u32 s83, s83, 0x100
	s_addc_u32 s84, s84, 0
	s_cmp_gt_u32 s85, 13

; #define PG8_STAGE(bufoff, gbase, voff) do { _Pragma("unroll") for (int _i = 0; _i < 2; ++_i) \
;         __builtin_amdgcn_global_load_lds((const unsigned*)((const char*)(gbase) + (voff)[_i]), (LAS unsigned*)(lds + (bufoff) + ldsw + _i * 8192), 16, 0, 0); } while (0)
; #define PG8_LDA(dst, b, h) do { _Pragma("unroll") for (int m = 0; m < 4; ++m) _Pragma("unroll") for (int k = 0; k < 2; ++k) dst[m][k] = *(const LAS bf16x8*)(lds + PG8_SA(b, h) + aoff + m * 2048 + k * 1024); } while (0)
; #define PG8_LDB(dst, b, h) do { _Pragma("unroll") for (int n = 0; n < 2; ++n) _Pragma("unroll") for (int k = 0; k < 2; ++k) dst[n][k] = *(const LAS bf16x8*)(lds + PG8_SB(b, h) + boff + n * 2048 + k * 1024); } while (0)
; #define PG8_MMA(ai, bj, At, Bt) do { __builtin_amdgcn_s_setprio(1); _Pragma("unroll") for (int m = 0; m < 4; ++m) _Pragma("unroll") for (int n = 0; n < 2; ++n) _Pragma("unroll") for (int k = 0; k < 2; ++k) \
;         acc[ai][bj][m][n] = __builtin_amdgcn_mfma_f32_16x16x32_bf16(Bt[n][k], At[m][k], acc[ai][bj][m][n], 0, 0, 0); __builtin_amdgcn_s_setprio(0); } while (0)
; #define PG8_BAR __builtin_amdgcn_s_barrier()
; template <class Epi>
; __device__ __forceinline__ void gemm_phase(LAS unsigned char* lds, const Gemm g, const StaticOrder& S, const Epi& E) {
;     ...
;         const bool has_next = S.next(ui + 1, nxt);
;         const char* nA = has_next ? (const char*)g.A + (size_t)nxt.pm * tstepA : cA; const char* nB = has_next ? (const char*)g.Bt + (size_t)nxt.pn * tstepB : cB;
; #pragma nounroll
;         for (int t = 0; t < nt; t += 2) {
;             const bool last = (t == nt - 2);
;             const char* a1 = cA + (size_t)(t + 1) * kstep;
;             const char* a2 = last ? nA : cA + (size_t)(t + 2) * kstep; const char* b2 = last ? nB : cB + (size_t)(t + 2) * kstep;
;             const char* a3 = a2 + kstep; const char* b3 = b2 + kstep;
;             PG8_LDB(B0, 0, 0); PG8_LDB(B1, 0, 1); PG8_SCHED; PG8_LDA(At, 0, 0); PG8_STAGE(PG8_SA(1, 1), a1 + hstepA, voffA);
;             PG8_WAIT_V(8); PG8_WAIT_L(0); PG8_BAR; PG8_MMA(0, 0, At, B0); PG8_MMA(0, 1, At, B1); PG8_BAR; PG8_SCHED;
;             PG8_LDA(At, 0, 1); PG8_STAGE(PG8_SB(0, 0), b2, voffB); PG8_STAGE(PG8_SB(0, 1), b2 + hstepB, voffB); PG8_STAGE(PG8_SA(0, 0), a2, voffA);
;             PG8_WAIT_V(8); PG8_WAIT_L(0); PG8_BAR; PG8_MMA(1, 0, At, B0); PG8_MMA(1, 1, At, B1); PG8_BAR; PG8_SCHED;
.LBB0_1017:
	s_ashr_i32 s35, s34, 31
	s_lshl_b64 s[38:39], s[34:35], 19
	s_add_u32 s38, s24, s38
	s_addc_u32 s39, s25, s39
	s_and_b64 s[42:43], s[4:5], exec
	s_cselect_b32 s7, s39, s55
	s_cselect_b32 s35, s38, s54
	s_ashr_i32 s23, s22, 31
	s_lshl_b64 s[42:43], s[22:23], 19
	s_add_u32 s42, s33, s42
	s_addc_u32 s43, s64, s43
	s_and_b64 s[62:63], s[4:5], exec
	s_cselect_b32 s23, s43, s57
	s_cselect_b32 s53, s42, s56
	s_add_u32 s54, s54, 0x40080
	s_addc_u32 s55, s55, 0
	s_add_u32 s83, s56, 0x100
	s_nop 0
	s_addc_u32 s84, s57, 0
	s_mov_b32 s85, -2
	v_lshl_add_u32 v248, s6, 8, v227
	v_add_u32_e32 v248, s74, v248
	v_ashrrev_i32_e32 v249, 31, v248
	v_lshl_add_u64 v[248:249], v[248:249], 2, s[10:11]
	global_load_dword v240, v[248:249], off
	global_load_dword v241, v[248:249], off offset:64
	global_load_dword v242, v[248:249], off offset:128
	global_load_dword v243, v[248:249], off offset:192
	global_load_dword v244, v[248:249], off offset:512
	global_load_dword v245, v[248:249], off offset:576
	global_load_dword v246, v[248:249], off offset:640
	global_load_dword v247, v[248:249], off offset:704
	ds_read_b128 v[0:3], v230
	ds_read_b128 v[4:7], v230 offset:1024
	ds_read_b128 v[8:11], v230 offset:2048
	ds_read_b128 v[12:15], v230 offset:3072
	ds_read_b128 v[144:147], v231
	ds_read_b128 v[148:151], v231 offset:1024
	ds_read_b128 v[152:155], v231 offset:2048
	ds_read_b128 v[156:159], v231 offset:3072
	s_add_u32 s56, s54, 0xfffc0080
	s_addc_u32 s57, s55, -1
	s_cmp_eq_u32 s85, 12
	s_cselect_b32 s63, s7, s57
	s_cselect_b32 s62, s35, s56
	s_cselect_b32 s57, s23, s84
	s_cselect_b32 s56, s53, s83
	v_lshl_add_u64 v[212:213], s[54:55], 0, v[188:189]
	s_add_i32 m0, s68, 0xc000
	ds_read_b128 v[160:163], v232
	ds_read_b128 v[164:167], v232 offset:1024
	ds_read_b128 v[168:171], v232 offset:2048
	ds_read_b128 v[172:175], v232 offset:3072
	ds_read_b128 v[196:199], v232 offset:4096
	ds_read_b128 v[200:203], v232 offset:5120
	ds_read_b128 v[204:207], v232 offset:6144
	ds_read_b128 v[208:211], v232 offset:7168
	global_load_lds_dwordx4 v[212:213], off
	v_lshl_add_u64 v[212:213], s[54:55], 0, v[190:191]
	s_add_i32 m0, s68, 0xe000
	s_nop 0
	global_load_lds_dwordx4 v[212:213], off
	s_waitcnt vmcnt(8)
	s_waitcnt lgkmcnt(0)
	s_barrier
	s_setprio 1
	s_waitcnt lgkmcnt(0)
	v_mfma_f32_16x16x32_bf16 v[140:143], v[0:3], v[160:163], 0
	v_mfma_f32_16x16x32_bf16 v[132:135], v[8:11], v[160:163], 0
	v_mfma_f32_16x16x32_bf16 v[124:127], v[0:3], v[168:171], 0
	v_mfma_f32_16x16x32_bf16 v[120:123], v[8:11], v[168:171], 0
	v_mfma_f32_16x16x32_bf16 v[108:111], v[0:3], v[196:199], 0
	v_mfma_f32_16x16x32_bf16 v[104:107], v[8:11], v[196:199], 0
	v_mfma_f32_16x16x32_bf16 v[92:95], v[0:3], v[204:207], 0
	v_mfma_f32_16x16x32_bf16 v[88:91], v[8:11], v[204:207], 0
	v_mfma_f32_16x16x32_bf16 v[140:143], v[4:7], v[164:167], v[140:143]
	v_mfma_f32_16x16x32_bf16 v[132:135], v[12:15], v[164:167], v[132:135]
	v_mfma_f32_16x16x32_bf16 v[124:127], v[4:7], v[172:175], v[124:127]
	v_mfma_f32_16x16x32_bf16 v[120:123], v[12:15], v[172:175], v[120:123]
	v_mfma_f32_16x16x32_bf16 v[108:111], v[4:7], v[200:203], v[108:111]
	v_mfma_f32_16x16x32_bf16 v[104:107], v[12:15], v[200:203], v[104:107]
	v_mfma_f32_16x16x32_bf16 v[92:95], v[4:7], v[208:211], v[92:95]
	v_mfma_f32_16x16x32_bf16 v[88:91], v[12:15], v[208:211], v[88:91]
	s_setprio 0
	s_setprio 1
	v_mfma_f32_16x16x32_bf16 v[136:139], v[144:147], v[160:163], 0
	v_mfma_f32_16x16x32_bf16 v[128:131], v[152:155], v[160:163], 0
	v_mfma_f32_16x16x32_bf16 v[116:119], v[144:147], v[168:171], 0
	v_mfma_f32_16x16x32_bf16 v[112:115], v[152:155], v[168:171], 0
	v_mfma_f32_16x16x32_bf16 v[100:103], v[144:147], v[196:199], 0
	v_mfma_f32_16x16x32_bf16 v[96:99], v[152:155], v[196:199], 0
	v_mfma_f32_16x16x32_bf16 v[84:87], v[144:147], v[204:207], 0
	v_mfma_f32_16x16x32_bf16 v[80:83], v[152:155], v[204:207], 0
	v_mfma_f32_16x16x32_bf16 v[136:139], v[148:151], v[164:167], v[136:139]
	v_mfma_f32_16x16x32_bf16 v[128:131], v[156:159], v[164:167], v[128:131]
	v_mfma_f32_16x16x32_bf16 v[116:119], v[148:151], v[172:175], v[116:119]
	v_mfma_f32_16x16x32_bf16 v[112:115], v[156:159], v[172:175], v[112:115]
	v_mfma_f32_16x16x32_bf16 v[100:103], v[148:151], v[200:203], v[100:103]
	v_mfma_f32_16x16x32_bf16 v[96:99], v[156:159], v[200:203], v[96:99]
	v_mfma_f32_16x16x32_bf16 v[84:87], v[148:151], v[208:211], v[84:87]
	v_mfma_f32_16x16x32_bf16 v[80:83], v[156:159], v[208:211], v[80:83]
	s_setprio 0
	s_barrier
	s_add_i32 s86, s81, s65
	v_lshl_add_u64 v[212:213], s[56:57], 0, v[180:181]
	s_mov_b32 m0, s86
	ds_read_b128 v[160:163], v232 offset:16384
	ds_read_b128 v[164:167], v232 offset:17408
	ds_read_b128 v[168:171], v232 offset:18432
	ds_read_b128 v[172:175], v232 offset:19456
	ds_read_b128 v[196:199], v232 offset:20480
	ds_read_b128 v[200:203], v232 offset:21504
	ds_read_b128 v[204:207], v232 offset:22528
	ds_read_b128 v[208:211], v232 offset:23552
	global_load_lds_dwordx4 v[212:213], off
	s_add_i32 m0, s86, 0x2000
	s_add_u32 s86, s56, 0x40000
	v_lshl_add_u64 v[214:215], s[56:57], 0, v[184:185]
	s_addc_u32 s87, s57, 0
	s_add_i32 s88, s82, s65
	global_load_lds_dwordx4 v[214:215], off
	v_lshl_add_u64 v[216:217], s[86:87], 0, v[180:181]
	s_mov_b32 m0, s88
	v_lshl_add_u64 v[218:219], s[62:63], 0, v[182:183]
	global_load_lds_dwordx4 v[216:217], off
	v_lshl_add_u64 v[216:217], s[86:87], 0, v[184:185]
	s_add_i32 m0, s88, 0x2000
	s_nop 0
	global_load_lds_dwordx4 v[216:217], off
	v_lshl_add_u64 v[216:217], s[62:63], 0, v[178:179]
	s_mov_b32 m0, s68
	s_nop 0
	global_load_lds_dwordx4 v[216:217], off
	s_mov_b32 m0, s69
	s_nop 0
	global_load_lds_dwordx4 v[218:219], off
	s_waitcnt vmcnt(8)
	s_waitcnt lgkmcnt(0)
	s_barrier
; #define PG8_STAGE(bufoff, gbase, voff) do { _Pragma("unroll") for (int _i = 0; _i < 2; ++_i) \
;         __builtin_amdgcn_global_load_lds((const unsigned*)((const char*)(gbase) + (voff)[_i]), (LAS unsigned*)(lds + (bufoff) + ldsw + _i * 8192), 16, 0, 0); } while (0)
; #define PG8_LDA(dst, b, h) do { _Pragma("unroll") for (int m = 0; m < 4; ++m) _Pragma("unroll") for (int k = 0; k < 2; ++k) dst[m][k] = *(const LAS bf16x8*)(lds + PG8_SA(b, h) + aoff + m * 2048 + k * 1024); } while (0)
; #define PG8_LDB(dst, b, h) do { _Pragma("unroll") for (int n = 0; n < 2; ++n) _Pragma("unroll") for (int k = 0; k < 2; ++k) dst[n][k] = *(const LAS bf16x8*)(lds + PG8_SB(b, h) + boff + n * 2048 + k * 1024); } while (0)
; #define PG8_MMA(ai, bj, At, Bt) do { __builtin_amdgcn_s_setprio(1); _Pragma("unroll") for (int m = 0; m < 4; ++m) _Pragma("unroll") for (int n = 0; n < 2; ++n) _Pragma("unroll") for (int k = 0; k < 2; ++k) \
;         acc[ai][bj][m][n] = __builtin_amdgcn_mfma_f32_16x16x32_bf16(Bt[n][k], At[m][k], acc[ai][bj][m][n], 0, 0, 0); __builtin_amdgcn_s_setprio(0); } while (0)
; #define PG8_WAIT_V(n) asm volatile("s_waitcnt vmcnt(" #n ")" ::: "memory")
; #define PG8_WAIT_L(n) asm volatile("s_waitcnt lgkmcnt(" #n ")" ::: "memory")
; #define PG8_BAR __builtin_amdgcn_s_barrier()
; #define PG8_SCHED __builtin_amdgcn_sched_barrier(0)
; template <class Epi>
; __device__ __forceinline__ void gemm_phase(LAS unsigned char* lds, const Gemm g, const StaticOrder& S, const Epi& E) {
;     ...
;             PG8_WAIT_V(8); PG8_WAIT_L(0); PG8_BAR; PG8_MMA(1, 0, At, B0); PG8_MMA(1, 1, At, B1); PG8_BAR; PG8_SCHED;
;             PG8_LDB(B0, 1, 0); PG8_LDB(B1, 1, 1); PG8_SCHED; PG8_LDA(At, 1, 0); PG8_STAGE(PG8_SA(0, 1), a2 + hstepA, voffA);
;             PG8_WAIT_V(8); PG8_WAIT_L(0); PG8_BAR; PG8_MMA(0, 0, At, B0); PG8_MMA(0, 1, At, B1); PG8_BAR; PG8_SCHED;
;             PG8_LDA(At, 1, 1); PG8_STAGE(PG8_SB(1, 0), b3, voffB); PG8_STAGE(PG8_SB(1, 1), b3 + hstepB, voffB); PG8_STAGE(PG8_SA(1, 0), a3, voffA);
;             PG8_WAIT_V(8); PG8_WAIT_L(0); PG8_BAR; PG8_MMA(1, 0, At, B0); PG8_MMA(1, 1, At, B1); PG8_BAR; PG8_SCHED;
	s_setprio 1
	s_waitcnt lgkmcnt(0)
	v_mfma_f32_16x16x32_bf16 v[76:79], v[0:3], v[160:163], 0
	v_mfma_f32_16x16x32_bf16 v[72:75], v[8:11], v[160:163], 0
	v_mfma_f32_16x16x32_bf16 v[60:63], v[0:3], v[168:171], 0
	v_mfma_f32_16x16x32_bf16 v[56:59], v[8:11], v[168:171], 0
	v_mfma_f32_16x16x32_bf16 v[44:47], v[0:3], v[196:199], 0
	v_mfma_f32_16x16x32_bf16 v[40:43], v[8:11], v[196:199], 0
	v_mfma_f32_16x16x32_bf16 v[0:3], v[0:3], v[204:207], 0
	v_mfma_f32_16x16x32_bf16 v[76:79], v[4:7], v[164:167], v[76:79]
	v_mfma_f32_16x16x32_bf16 v[72:75], v[12:15], v[164:167], v[72:75]
	v_mfma_f32_16x16x32_bf16 v[60:63], v[4:7], v[172:175], v[60:63]
	v_mfma_f32_16x16x32_bf16 v[56:59], v[12:15], v[172:175], v[56:59]
	v_mfma_f32_16x16x32_bf16 v[44:47], v[4:7], v[200:203], v[44:47]
	v_mfma_f32_16x16x32_bf16 v[40:43], v[12:15], v[200:203], v[40:43]
	v_mfma_f32_16x16x32_bf16 v[0:3], v[4:7], v[208:211], v[0:3]
	v_mfma_f32_16x16x32_bf16 v[4:7], v[8:11], v[204:207], 0
	v_mfma_f32_16x16x32_bf16 v[4:7], v[12:15], v[208:211], v[4:7]
	s_setprio 0
	s_setprio 1
	v_mfma_f32_16x16x32_bf16 v[20:23], v[144:147], v[168:171], 0
	v_mfma_f32_16x16x32_bf16 v[52:55], v[148:151], v[172:175], v[20:23]
	v_mfma_f32_16x16x32_bf16 v[20:23], v[152:155], v[168:171], 0
	v_mfma_f32_16x16x32_bf16 v[48:51], v[156:159], v[172:175], v[20:23]
	v_mfma_f32_16x16x32_bf16 v[20:23], v[144:147], v[196:199], 0
	v_mfma_f32_16x16x32_bf16 v[36:39], v[148:151], v[200:203], v[20:23]
	v_mfma_f32_16x16x32_bf16 v[20:23], v[152:155], v[196:199], 0
	v_mfma_f32_16x16x32_bf16 v[32:35], v[156:159], v[200:203], v[20:23]
	v_mfma_f32_16x16x32_bf16 v[20:23], v[144:147], v[204:207], 0
	v_mfma_f32_16x16x32_bf16 v[16:19], v[152:155], v[204:207], 0
	v_mfma_f32_16x16x32_bf16 v[8:11], v[144:147], v[160:163], 0
	v_mfma_f32_16x16x32_bf16 v[12:15], v[152:155], v[160:163], 0
	v_mfma_f32_16x16x32_bf16 v[24:27], v[148:151], v[208:211], v[20:23]
	v_mfma_f32_16x16x32_bf16 v[16:19], v[156:159], v[208:211], v[16:19]
	v_mfma_f32_16x16x32_bf16 v[8:11], v[148:151], v[164:167], v[8:11]
	v_mfma_f32_16x16x32_bf16 v[12:15], v[156:159], v[164:167], v[12:15]
	s_setprio 0
	s_barrier
	s_add_i32 s86, 0, 0x18000
	s_add_i32 s87, 0, 0x1c000
	v_add_u32_e32 v68, s86, v229
	v_add_u32_e32 v156, s87, v229
	ds_read_b128 v[20:23], v68
	ds_read_b128 v[28:31], v68 offset:1024
	ds_read_b128 v[64:67], v68 offset:2048
	ds_read_b128 v[68:71], v68 offset:3072
	ds_read_b128 v[144:147], v156
	ds_read_b128 v[148:151], v156 offset:1024
	ds_read_b128 v[152:155], v156 offset:2048
	ds_read_b128 v[156:159], v156 offset:3072
	s_add_u32 s62, s62, 0x40000
	s_addc_u32 s63, s63, 0
	s_mov_b32 m0, s70
	v_lshl_add_u64 v[220:221], s[62:63], 0, v[178:179]
	ds_read_b128 v[160:163], v232 offset:32768
	ds_read_b128 v[164:167], v232 offset:33792
	ds_read_b128 v[168:171], v232 offset:34816
	ds_read_b128 v[172:175], v232 offset:35840
	ds_read_b128 v[196:199], v232 offset:36864
	ds_read_b128 v[200:203], v232 offset:37888
	ds_read_b128 v[204:207], v232 offset:38912
	ds_read_b128 v[208:211], v232 offset:39936
	global_load_lds_dwordx4 v[220:221], off
	v_lshl_add_u64 v[220:221], s[62:63], 0, v[182:183]
	s_mov_b32 m0, s71
	s_nop 0
	global_load_lds_dwordx4 v[220:221], off
	s_waitcnt vmcnt(8)
	s_waitcnt lgkmcnt(0)
	s_barrier
	s_setprio 1
	s_waitcnt lgkmcnt(0)
	v_mfma_f32_16x16x32_bf16 v[140:143], v[20:23], v[160:163], v[140:143]
	v_mfma_f32_16x16x32_bf16 v[132:135], v[64:67], v[160:163], v[132:135]
	v_mfma_f32_16x16x32_bf16 v[124:127], v[20:23], v[168:171], v[124:127]
	v_mfma_f32_16x16x32_bf16 v[120:123], v[64:67], v[168:171], v[120:123]
	v_mfma_f32_16x16x32_bf16 v[108:111], v[20:23], v[196:199], v[108:111]
	v_mfma_f32_16x16x32_bf16 v[104:107], v[64:67], v[196:199], v[104:107]
	v_mfma_f32_16x16x32_bf16 v[92:95], v[20:23], v[204:207], v[92:95]
	v_mfma_f32_16x16x32_bf16 v[88:91], v[64:67], v[204:207], v[88:91]
	v_mfma_f32_16x16x32_bf16 v[140:143], v[28:31], v[164:167], v[140:143]
	v_mfma_f32_16x16x32_bf16 v[132:135], v[68:71], v[164:167], v[132:135]
	v_mfma_f32_16x16x32_bf16 v[124:127], v[28:31], v[172:175], v[124:127]
	v_mfma_f32_16x16x32_bf16 v[120:123], v[68:71], v[172:175], v[120:123]
	v_mfma_f32_16x16x32_bf16 v[108:111], v[28:31], v[200:203], v[108:111]
	v_mfma_f32_16x16x32_bf16 v[104:107], v[68:71], v[200:203], v[104:107]
	v_mfma_f32_16x16x32_bf16 v[92:95], v[28:31], v[208:211], v[92:95]
	v_mfma_f32_16x16x32_bf16 v[88:91], v[68:71], v[208:211], v[88:91]
	s_setprio 0
	s_setprio 1
	v_mfma_f32_16x16x32_bf16 v[136:139], v[144:147], v[160:163], v[136:139]
	v_mfma_f32_16x16x32_bf16 v[128:131], v[152:155], v[160:163], v[128:131]
	v_mfma_f32_16x16x32_bf16 v[116:119], v[144:147], v[168:171], v[116:119]
	v_mfma_f32_16x16x32_bf16 v[112:115], v[152:155], v[168:171], v[112:115]
	v_mfma_f32_16x16x32_bf16 v[100:103], v[144:147], v[196:199], v[100:103]
	v_mfma_f32_16x16x32_bf16 v[96:99], v[152:155], v[196:199], v[96:99]
	v_mfma_f32_16x16x32_bf16 v[84:87], v[144:147], v[204:207], v[84:87]
	v_mfma_f32_16x16x32_bf16 v[80:83], v[152:155], v[204:207], v[80:83]
	v_mfma_f32_16x16x32_bf16 v[136:139], v[148:151], v[164:167], v[136:139]
	v_mfma_f32_16x16x32_bf16 v[128:131], v[156:159], v[164:167], v[128:131]
	v_mfma_f32_16x16x32_bf16 v[116:119], v[148:151], v[172:175], v[116:119]
	v_mfma_f32_16x16x32_bf16 v[112:115], v[156:159], v[172:175], v[112:115]
	v_mfma_f32_16x16x32_bf16 v[100:103], v[148:151], v[200:203], v[100:103]
	v_mfma_f32_16x16x32_bf16 v[96:99], v[156:159], v[200:203], v[96:99]
	v_mfma_f32_16x16x32_bf16 v[84:87], v[148:151], v[208:211], v[84:87]
	v_mfma_f32_16x16x32_bf16 v[80:83], v[156:159], v[208:211], v[80:83]
	s_setprio 0
	s_barrier
; #define PG8_STAGE(bufoff, gbase, voff) do { _Pragma("unroll") for (int _i = 0; _i < 2; ++_i) \
;         __builtin_amdgcn_global_load_lds((const unsigned*)((const char*)(gbase) + (voff)[_i]), (LAS unsigned*)(lds + (bufoff) + ldsw + _i * 8192), 16, 0, 0); } while (0)
; #define PG8_LDA(dst, b, h) do { _Pragma("unroll") for (int m = 0; m < 4; ++m) _Pragma("unroll") for (int k = 0; k < 2; ++k) dst[m][k] = *(const LAS bf16x8*)(lds + PG8_SA(b, h) + aoff + m * 2048 + k * 1024); } while (0)
; #define PG8_MMA(ai, bj, At, Bt) do { __builtin_amdgcn_s_setprio(1); _Pragma("unroll") for (int m = 0; m < 4; ++m) _Pragma("unroll") for (int n = 0; n < 2; ++n) _Pragma("unroll") for (int k = 0; k < 2; ++k) \
;         acc[ai][bj][m][n] = __builtin_amdgcn_mfma_f32_16x16x32_bf16(Bt[n][k], At[m][k], acc[ai][bj][m][n], 0, 0, 0); __builtin_amdgcn_s_setprio(0); } while (0)
; #define PG8_WAIT_V(n) asm volatile("s_waitcnt vmcnt(" #n ")" ::: "memory")
; #define PG8_WAIT_L(n) asm volatile("s_waitcnt lgkmcnt(" #n ")" ::: "memory")
; #define PG8_BAR __builtin_amdgcn_s_barrier()
; #define PG8_SCHED __builtin_amdgcn_sched_barrier(0)
; template <class Epi>
; __device__ __forceinline__ void gemm_phase(LAS unsigned char* lds, const Gemm g, const StaticOrder& S, const Epi& E) {
;     ...
;             PG8_LDA(At, 1, 1); PG8_STAGE(PG8_SB(1, 0), b3, voffB); PG8_STAGE(PG8_SB(1, 1), b3 + hstepB, voffB); PG8_STAGE(PG8_SA(1, 0), a3, voffA);
;             PG8_WAIT_V(8); PG8_WAIT_L(0); PG8_BAR; PG8_MMA(1, 0, At, B0); PG8_MMA(1, 1, At, B1); PG8_BAR; PG8_SCHED;
;         }
	s_add_i32 s62, s86, s65
	v_lshl_add_u64 v[212:213], v[212:213], 0, s[16:17]
	s_mov_b32 m0, s62
	ds_read_b128 v[160:163], v232 offset:49152
	ds_read_b128 v[164:167], v232 offset:50176
	ds_read_b128 v[168:171], v232 offset:51200
	ds_read_b128 v[172:175], v232 offset:52224
	ds_read_b128 v[196:199], v232 offset:53248
	ds_read_b128 v[200:203], v232 offset:54272
	ds_read_b128 v[204:207], v232 offset:55296
	ds_read_b128 v[208:211], v232 offset:56320
	global_load_lds_dwordx4 v[212:213], off
	s_add_i32 m0, s62, 0x2000
	s_add_u32 s56, s56, 0x40080
	v_lshl_add_u64 v[212:213], v[214:215], 0, s[16:17]
	s_addc_u32 s57, s57, 0
	s_add_i32 s62, s87, s65
	global_load_lds_dwordx4 v[212:213], off
	v_lshl_add_u64 v[212:213], s[56:57], 0, v[180:181]
	s_mov_b32 m0, s62
	s_nop 0
	global_load_lds_dwordx4 v[212:213], off
	v_lshl_add_u64 v[212:213], s[56:57], 0, v[184:185]
	s_add_i32 m0, s62, 0x2000
	s_nop 0
	global_load_lds_dwordx4 v[212:213], off
	v_lshl_add_u64 v[212:213], v[216:217], 0, s[16:17]
	s_mov_b32 m0, s76
	s_nop 0
	global_load_lds_dwordx4 v[212:213], off
	v_lshl_add_u64 v[212:213], v[218:219], 0, s[16:17]
	s_mov_b32 m0, s77
	s_nop 0
	global_load_lds_dwordx4 v[212:213], off
	s_waitcnt vmcnt(8)
	s_waitcnt lgkmcnt(0)
	s_barrier
	s_setprio 1
	s_waitcnt lgkmcnt(0)
	v_mfma_f32_16x16x32_bf16 v[76:79], v[20:23], v[160:163], v[76:79]
	v_mfma_f32_16x16x32_bf16 v[60:63], v[20:23], v[168:171], v[60:63]
	v_mfma_f32_16x16x32_bf16 v[44:47], v[20:23], v[196:199], v[44:47]
	v_mfma_f32_16x16x32_bf16 v[0:3], v[20:23], v[204:207], v[0:3]
	v_mfma_f32_16x16x32_bf16 v[76:79], v[28:31], v[164:167], v[76:79]
	v_mfma_f32_16x16x32_bf16 v[72:75], v[64:67], v[160:163], v[72:75]
	v_mfma_f32_16x16x32_bf16 v[60:63], v[28:31], v[172:175], v[60:63]
	v_mfma_f32_16x16x32_bf16 v[56:59], v[64:67], v[168:171], v[56:59]
	v_mfma_f32_16x16x32_bf16 v[44:47], v[28:31], v[200:203], v[44:47]
	v_mfma_f32_16x16x32_bf16 v[40:43], v[64:67], v[196:199], v[40:43]
	v_mfma_f32_16x16x32_bf16 v[28:31], v[28:31], v[208:211], v[0:3]
	v_mfma_f32_16x16x32_bf16 v[0:3], v[64:67], v[204:207], v[4:7]
	v_mfma_f32_16x16x32_bf16 v[72:75], v[68:71], v[164:167], v[72:75]
	v_mfma_f32_16x16x32_bf16 v[56:59], v[68:71], v[172:175], v[56:59]
	v_mfma_f32_16x16x32_bf16 v[40:43], v[68:71], v[200:203], v[40:43]
	v_mfma_f32_16x16x32_bf16 v[20:23], v[68:71], v[208:211], v[0:3]
	s_setprio 0
	s_setprio 1
	v_mfma_f32_16x16x32_bf16 v[0:3], v[144:147], v[160:163], v[8:11]
	v_mfma_f32_16x16x32_bf16 v[68:71], v[148:151], v[164:167], v[0:3]
	v_mfma_f32_16x16x32_bf16 v[0:3], v[152:155], v[160:163], v[12:15]
	v_mfma_f32_16x16x32_bf16 v[64:67], v[156:159], v[164:167], v[0:3]
	v_mfma_f32_16x16x32_bf16 v[0:3], v[144:147], v[168:171], v[52:55]
	v_mfma_f32_16x16x32_bf16 v[52:55], v[148:151], v[172:175], v[0:3]
	v_mfma_f32_16x16x32_bf16 v[0:3], v[152:155], v[168:171], v[48:51]
	v_mfma_f32_16x16x32_bf16 v[48:51], v[156:159], v[172:175], v[0:3]
	v_mfma_f32_16x16x32_bf16 v[0:3], v[144:147], v[196:199], v[36:39]
	v_mfma_f32_16x16x32_bf16 v[36:39], v[148:151], v[200:203], v[0:3]
	v_mfma_f32_16x16x32_bf16 v[0:3], v[152:155], v[196:199], v[32:35]
	v_mfma_f32_16x16x32_bf16 v[32:35], v[156:159], v[200:203], v[0:3]
	v_mfma_f32_16x16x32_bf16 v[0:3], v[144:147], v[204:207], v[24:27]
	v_mfma_f32_16x16x32_bf16 v[24:27], v[148:151], v[208:211], v[0:3]
	v_mfma_f32_16x16x32_bf16 v[0:3], v[152:155], v[204:207], v[16:19]
	v_mfma_f32_16x16x32_bf16 v[16:19], v[156:159], v[208:211], v[0:3]
	s_setprio 0
	s_barrier
	s_add_i32 s85, s85, 2
	s_add_u32 s54, s54, 0x100
	s_addc_u32 s55, s55, 0
	s_add_u32 s83, s83, 0x100
	s_addc_u32 s84, s84, 0
	s_cmp_gt_u32 s85, 13
